# removed 18 duplicate s_waitcnt in the GEMM main loops on top of the previous version
# baseline (speedup 1.0000x reference)
; #define PG8_STAGE(bufoff, gbase, voff) do { _Pragma("unroll") for (int _i = 0; _i < 2; ++_i) \
;         __builtin_amdgcn_global_load_lds((const unsigned*)((const char*)(gbase) + (voff)[_i]), (PG8_LAS unsigned*)(lds + (bufoff) + ldsw + _i * 8192), 16, 0, 0); } while (0)
; #define PG8_LDA(dst, b, h) do { _Pragma("unroll") for (int m = 0; m < 4; ++m) _Pragma("unroll") for (int k = 0; k < 2; ++k) dst[m][k] = *(const PG8_LAS bf16x8*)(lds + PG8_SA(b, h) + aoff + m * 2048 + k * 1024); } while (0)
; #define PG8_LDB(dst, b, h) do { _Pragma("unroll") for (int n = 0; n < 2; ++n) _Pragma("unroll") for (int k = 0; k < 2; ++k) dst[n][k] = *(const PG8_LAS bf16x8*)(lds + PG8_SB(b, h) + boff + n * 2048 + k * 1024); } while (0)
; #define PG8_MMA(ai, bj, At, Bt) do { __builtin_amdgcn_s_setprio(1); _Pragma("unroll") for (int m = 0; m < 4; ++m) _Pragma("unroll") for (int n = 0; n < 2; ++n) _Pragma("unroll") for (int k = 0; k < 2; ++k) \
;         acc[ai][bj][m][n] = __builtin_amdgcn_mfma_f32_16x16x32_bf16(Bt[n][k], At[m][k], acc[ai][bj][m][n], 0, 0, 0); __builtin_amdgcn_s_setprio(0); } while (0)
; #define PG8_WAIT_L(n) asm volatile("s_waitcnt lgkmcnt(" #n ")" ::: "memory")
; #define PG8_BAR __builtin_amdgcn_s_barrier()
; #define PG8_SCHED __builtin_amdgcn_sched_barrier(0)
; template <class Epi, class Sched>
; __device__ __forceinline__ void gemm_phase(PG8_LAS unsigned char* lds, const Gemm g, const Sched& S, const Epi& E) {
;     ...
;             PG8_LDB(B0, 0, 0); PG8_SCHED; PG8_LDA(At, 0, 0); PG8_STAGE(PG8_SA(1, 1), a1 + hstep, voffA);
;             PG8_WAIT_L(8); PG8_BAR; PG8_WAIT_L(0); PG8_MMA(0, 0, At, B0); PG8_BAR; PG8_SCHED;
;             PG8_LDB(B1, 0, 1); PG8_STAGE(PG8_SB(0, 0), b2, voffB);
;             PG8_BAR; PG8_WAIT_L(0); PG8_MMA(0, 1, At, B1); PG8_BAR;
;             PG8_LDA(At, 0, 1); PG8_STAGE(PG8_SA(0, 0), a2, voffA);
;             PG8_BAR; PG8_WAIT_L(0); PG8_MMA(1, 0, At, B0); PG8_BAR; PG8_SCHED;
.LBB0_1071:
	s_add_u32 s20, s18, 0xfffc0080
	s_addc_u32 s21, s19, -1
	s_add_i32 s51, 0, 0x10000
	v_add_u32_e32 v144, s51, v147
	ds_read_b128 v[150:153], v144
	ds_read_b128 v[154:157], v144 offset:1024
	ds_read_b128 v[176:179], v144 offset:2048
	ds_read_b128 v[180:183], v144 offset:3072
	s_cmp_eq_u32 s50, 12
	s_cselect_b32 s23, s13, s21
	s_cselect_b32 s22, s40, s20
	s_cselect_b32 s21, s11, s45
	s_cselect_b32 s20, s41, s44
	v_lshl_add_u64 v[144:145], s[18:19], 0, v[140:141]
	s_add_i32 m0, s29, 0xc000
	ds_read_b128 v[184:187], v149
	ds_read_b128 v[188:191], v149 offset:1024
	ds_read_b128 v[192:195], v149 offset:2048
	ds_read_b128 v[196:199], v149 offset:3072
	ds_read_b128 v[200:203], v149 offset:4096
	ds_read_b128 v[204:207], v149 offset:5120
	ds_read_b128 v[208:211], v149 offset:6144
	ds_read_b128 v[212:215], v149 offset:7168
	global_load_lds_dwordx4 v[144:145], off
	v_lshl_add_u64 v[144:145], s[18:19], 0, v[142:143]
	s_add_i32 m0, s29, 0xe000
	s_nop 0
	global_load_lds_dwordx4 v[144:145], off
	s_waitcnt lgkmcnt(8)
	s_barrier
	s_waitcnt lgkmcnt(0)
	v_mfma_f32_16x16x32_bf16 v[126:129], v[150:153], v[184:187], v[126:129]
	v_mfma_f32_16x16x32_bf16 v[122:125], v[176:179], v[184:187], v[122:125]
	v_mfma_f32_16x16x32_bf16 v[118:121], v[150:153], v[192:195], v[118:121]
	v_mfma_f32_16x16x32_bf16 v[110:113], v[176:179], v[192:195], v[110:113]
	v_mfma_f32_16x16x32_bf16 v[102:105], v[150:153], v[200:203], v[102:105]
	v_mfma_f32_16x16x32_bf16 v[94:97], v[176:179], v[200:203], v[94:97]
	v_mfma_f32_16x16x32_bf16 v[86:89], v[150:153], v[208:211], v[86:89]
	v_mfma_f32_16x16x32_bf16 v[78:81], v[176:179], v[208:211], v[78:81]
	v_mfma_f32_16x16x32_bf16 v[126:129], v[154:157], v[188:191], v[126:129]
	v_mfma_f32_16x16x32_bf16 v[122:125], v[180:183], v[188:191], v[122:125]
	v_mfma_f32_16x16x32_bf16 v[118:121], v[154:157], v[196:199], v[118:121]
	v_mfma_f32_16x16x32_bf16 v[110:113], v[180:183], v[196:199], v[110:113]
	v_mfma_f32_16x16x32_bf16 v[102:105], v[154:157], v[204:207], v[102:105]
	v_mfma_f32_16x16x32_bf16 v[94:97], v[180:183], v[204:207], v[94:97]
	v_mfma_f32_16x16x32_bf16 v[86:89], v[154:157], v[212:215], v[86:89]
	v_mfma_f32_16x16x32_bf16 v[78:81], v[180:183], v[212:215], v[78:81]
	s_barrier
	s_add_i32 s59, 0, 0x14000
	v_add_u32_e32 v144, s59, v147
	s_add_i32 s51, s51, s28
	ds_read_b128 v[216:219], v144
	ds_read_b128 v[220:223], v144 offset:1024
	ds_read_b128 v[224:227], v144 offset:2048
	ds_read_b128 v[228:231], v144 offset:3072
	v_lshl_add_u64 v[144:145], s[20:21], 0, v[0:1]
	s_mov_b32 m0, s51
	v_lshl_add_u64 v[158:159], s[20:21], 0, v[134:135]
	global_load_lds_dwordx4 v[144:145], off
	s_add_i32 m0, s51, 0x2000
	s_nop 0
	global_load_lds_dwordx4 v[158:159], off
	s_barrier
	s_waitcnt lgkmcnt(0)
	v_mfma_f32_16x16x32_bf16 v[114:117], v[216:219], v[184:187], v[114:117]
	v_mfma_f32_16x16x32_bf16 v[106:109], v[224:227], v[184:187], v[106:109]
	v_mfma_f32_16x16x32_bf16 v[98:101], v[216:219], v[192:195], v[98:101]
	v_mfma_f32_16x16x32_bf16 v[90:93], v[224:227], v[192:195], v[90:93]
	v_mfma_f32_16x16x32_bf16 v[82:85], v[216:219], v[200:203], v[82:85]
	v_mfma_f32_16x16x32_bf16 v[74:77], v[224:227], v[200:203], v[74:77]
	v_mfma_f32_16x16x32_bf16 v[70:73], v[216:219], v[208:211], v[70:73]
	v_mfma_f32_16x16x32_bf16 v[66:69], v[224:227], v[208:211], v[66:69]
	v_mfma_f32_16x16x32_bf16 v[114:117], v[220:223], v[188:191], v[114:117]
	v_mfma_f32_16x16x32_bf16 v[106:109], v[228:231], v[188:191], v[106:109]
	v_mfma_f32_16x16x32_bf16 v[98:101], v[220:223], v[196:199], v[98:101]
	v_mfma_f32_16x16x32_bf16 v[90:93], v[228:231], v[196:199], v[90:93]
	v_mfma_f32_16x16x32_bf16 v[82:85], v[220:223], v[204:207], v[82:85]
	v_mfma_f32_16x16x32_bf16 v[74:77], v[228:231], v[204:207], v[74:77]
	v_mfma_f32_16x16x32_bf16 v[70:73], v[220:223], v[212:215], v[70:73]
	v_mfma_f32_16x16x32_bf16 v[66:69], v[228:231], v[212:215], v[66:69]
	s_mov_b32 m0, s29
	v_lshl_add_u64 v[232:233], s[22:23], 0, v[138:139]
	s_barrier
	ds_read_b128 v[184:187], v149 offset:16384
	ds_read_b128 v[188:191], v149 offset:17408
	ds_read_b128 v[192:195], v149 offset:18432
	ds_read_b128 v[196:199], v149 offset:19456
	ds_read_b128 v[200:203], v149 offset:20480
	ds_read_b128 v[204:207], v149 offset:21504
	ds_read_b128 v[208:211], v149 offset:22528
	ds_read_b128 v[212:215], v149 offset:23552
	global_load_lds_dwordx4 v[232:233], off
	v_lshl_add_u64 v[234:235], s[22:23], 0, v[136:137]
	s_mov_b32 m0, s30
	s_nop 0
	global_load_lds_dwordx4 v[234:235], off
	s_barrier
	s_waitcnt lgkmcnt(0)
	v_mfma_f32_16x16x32_bf16 v[62:65], v[150:153], v[184:187], v[62:65]
	v_mfma_f32_16x16x32_bf16 v[58:61], v[176:179], v[184:187], v[58:61]
	v_mfma_f32_16x16x32_bf16 v[50:53], v[150:153], v[192:195], v[50:53]
	v_mfma_f32_16x16x32_bf16 v[42:45], v[176:179], v[192:195], v[42:45]
	v_mfma_f32_16x16x32_bf16 v[34:37], v[150:153], v[200:203], v[34:37]
	v_mfma_f32_16x16x32_bf16 v[26:29], v[176:179], v[200:203], v[26:29]
	v_mfma_f32_16x16x32_bf16 v[18:21], v[150:153], v[208:211], v[18:21]
	v_mfma_f32_16x16x32_bf16 v[10:13], v[176:179], v[208:211], v[10:13]
	v_mfma_f32_16x16x32_bf16 v[62:65], v[154:157], v[188:191], v[62:65]
	v_mfma_f32_16x16x32_bf16 v[58:61], v[180:183], v[188:191], v[58:61]
	v_mfma_f32_16x16x32_bf16 v[50:53], v[154:157], v[196:199], v[50:53]
	v_mfma_f32_16x16x32_bf16 v[42:45], v[180:183], v[196:199], v[42:45]
	v_mfma_f32_16x16x32_bf16 v[34:37], v[154:157], v[204:207], v[34:37]
	v_mfma_f32_16x16x32_bf16 v[26:29], v[180:183], v[204:207], v[26:29]
	v_mfma_f32_16x16x32_bf16 v[18:21], v[154:157], v[212:215], v[18:21]
	v_mfma_f32_16x16x32_bf16 v[10:13], v[180:183], v[212:215], v[10:13]
	s_barrier
; #define PG8_STAGE(bufoff, gbase, voff) do { _Pragma("unroll") for (int _i = 0; _i < 2; ++_i) \
;         __builtin_amdgcn_global_load_lds((const unsigned*)((const char*)(gbase) + (voff)[_i]), (PG8_LAS unsigned*)(lds + (bufoff) + ldsw + _i * 8192), 16, 0, 0); } while (0)
; #define PG8_LDA(dst, b, h) do { _Pragma("unroll") for (int m = 0; m < 4; ++m) _Pragma("unroll") for (int k = 0; k < 2; ++k) dst[m][k] = *(const PG8_LAS bf16x8*)(lds + PG8_SA(b, h) + aoff + m * 2048 + k * 1024); } while (0)
; #define PG8_LDB(dst, b, h) do { _Pragma("unroll") for (int n = 0; n < 2; ++n) _Pragma("unroll") for (int k = 0; k < 2; ++k) dst[n][k] = *(const PG8_LAS bf16x8*)(lds + PG8_SB(b, h) + boff + n * 2048 + k * 1024); } while (0)
; #define PG8_MMA(ai, bj, At, Bt) do { __builtin_amdgcn_s_setprio(1); _Pragma("unroll") for (int m = 0; m < 4; ++m) _Pragma("unroll") for (int n = 0; n < 2; ++n) _Pragma("unroll") for (int k = 0; k < 2; ++k) \
;         acc[ai][bj][m][n] = __builtin_amdgcn_mfma_f32_16x16x32_bf16(Bt[n][k], At[m][k], acc[ai][bj][m][n], 0, 0, 0); __builtin_amdgcn_s_setprio(0); } while (0)
; #define PG8_WAIT_V(n) asm volatile("s_waitcnt vmcnt(" #n ")" ::: "memory")
; #define PG8_WAIT_L(n) asm volatile("s_waitcnt lgkmcnt(" #n ")" ::: "memory")
; #define PG8_BAR __builtin_amdgcn_s_barrier()
; #define PG8_SCHED __builtin_amdgcn_sched_barrier(0)
; template <class Epi, class Sched>
; __device__ __forceinline__ void gemm_phase(PG8_LAS unsigned char* lds, const Gemm g, const Sched& S, const Epi& E) {
;     ...
;             PG8_STAGE(PG8_SB(0, 1), b2 + hstep, voffB);
;             PG8_WAIT_V(6); PG8_BAR; PG8_MMA(1, 1, At, B1); PG8_BAR;
;             PG8_LDB(B0, 1, 0); PG8_SCHED; PG8_LDA(At, 1, 0); PG8_STAGE(PG8_SA(0, 1), a2 + hstep, voffA);
;             PG8_WAIT_L(8); PG8_BAR; PG8_WAIT_L(0); PG8_MMA(0, 0, At, B0); PG8_BAR; PG8_SCHED;
;             PG8_LDB(B1, 1, 1); PG8_STAGE(PG8_SB(1, 0), b3, voffB);
	s_add_u32 s56, s20, 0x40000
	s_addc_u32 s57, s21, 0
	s_add_i32 s51, s59, s28
	v_lshl_add_u64 v[150:151], s[56:57], 0, v[0:1]
	s_mov_b32 m0, s51
	s_nop 0
	global_load_lds_dwordx4 v[150:151], off
	v_lshl_add_u64 v[150:151], s[56:57], 0, v[134:135]
	s_add_i32 m0, s51, 0x2000
	s_nop 0
	global_load_lds_dwordx4 v[150:151], off
	s_waitcnt vmcnt(6)
	s_barrier
	v_mfma_f32_16x16x32_bf16 v[54:57], v[216:219], v[184:187], v[54:57]
	v_mfma_f32_16x16x32_bf16 v[46:49], v[224:227], v[184:187], v[46:49]
	v_mfma_f32_16x16x32_bf16 v[38:41], v[216:219], v[192:195], v[38:41]
	v_mfma_f32_16x16x32_bf16 v[30:33], v[224:227], v[192:195], v[30:33]
	v_mfma_f32_16x16x32_bf16 v[22:25], v[216:219], v[200:203], v[22:25]
	v_mfma_f32_16x16x32_bf16 v[14:17], v[224:227], v[200:203], v[14:17]
	v_mfma_f32_16x16x32_bf16 v[6:9], v[216:219], v[208:211], v[6:9]
	v_mfma_f32_16x16x32_bf16 v[2:5], v[224:227], v[208:211], v[2:5]
	v_mfma_f32_16x16x32_bf16 v[54:57], v[220:223], v[188:191], v[54:57]
	v_mfma_f32_16x16x32_bf16 v[46:49], v[228:231], v[188:191], v[46:49]
	v_mfma_f32_16x16x32_bf16 v[38:41], v[220:223], v[196:199], v[38:41]
	v_mfma_f32_16x16x32_bf16 v[30:33], v[228:231], v[196:199], v[30:33]
	v_mfma_f32_16x16x32_bf16 v[22:25], v[220:223], v[204:207], v[22:25]
	v_mfma_f32_16x16x32_bf16 v[14:17], v[228:231], v[204:207], v[14:17]
	v_mfma_f32_16x16x32_bf16 v[6:9], v[220:223], v[212:215], v[6:9]
	v_mfma_f32_16x16x32_bf16 v[2:5], v[228:231], v[212:215], v[2:5]
	s_add_i32 s51, 0, 0x18000
	v_add_u32_e32 v175, s51, v147
	s_barrier
	ds_read_b128 v[150:153], v175
	ds_read_b128 v[154:157], v175 offset:1024
	ds_read_b128 v[176:179], v175 offset:2048
	ds_read_b128 v[180:183], v175 offset:3072
	s_add_u32 s22, s22, 0x40000
	s_addc_u32 s23, s23, 0
	s_mov_b32 m0, s31
	v_lshl_add_u64 v[216:217], s[22:23], 0, v[138:139]
	ds_read_b128 v[184:187], v149 offset:32768
	ds_read_b128 v[188:191], v149 offset:33792
	ds_read_b128 v[192:195], v149 offset:34816
	ds_read_b128 v[196:199], v149 offset:35840
	ds_read_b128 v[200:203], v149 offset:36864
	ds_read_b128 v[204:207], v149 offset:37888
	ds_read_b128 v[208:211], v149 offset:38912
	ds_read_b128 v[212:215], v149 offset:39936
	global_load_lds_dwordx4 v[216:217], off
	v_lshl_add_u64 v[216:217], s[22:23], 0, v[136:137]
	s_mov_b32 m0, s34
	s_nop 0
	global_load_lds_dwordx4 v[216:217], off
	s_waitcnt lgkmcnt(8)
	s_barrier
	s_waitcnt lgkmcnt(0)
	v_mfma_f32_16x16x32_bf16 v[126:129], v[150:153], v[184:187], v[126:129]
	v_mfma_f32_16x16x32_bf16 v[122:125], v[176:179], v[184:187], v[122:125]
	v_mfma_f32_16x16x32_bf16 v[118:121], v[150:153], v[192:195], v[118:121]
	v_mfma_f32_16x16x32_bf16 v[110:113], v[176:179], v[192:195], v[110:113]
	v_mfma_f32_16x16x32_bf16 v[102:105], v[150:153], v[200:203], v[102:105]
	v_mfma_f32_16x16x32_bf16 v[94:97], v[176:179], v[200:203], v[94:97]
	v_mfma_f32_16x16x32_bf16 v[86:89], v[150:153], v[208:211], v[86:89]
	v_mfma_f32_16x16x32_bf16 v[78:81], v[176:179], v[208:211], v[78:81]
	v_mfma_f32_16x16x32_bf16 v[126:129], v[154:157], v[188:191], v[126:129]
	v_mfma_f32_16x16x32_bf16 v[122:125], v[180:183], v[188:191], v[122:125]
	v_mfma_f32_16x16x32_bf16 v[118:121], v[154:157], v[196:199], v[118:121]
	v_mfma_f32_16x16x32_bf16 v[110:113], v[180:183], v[196:199], v[110:113]
	v_mfma_f32_16x16x32_bf16 v[102:105], v[154:157], v[204:207], v[102:105]
	v_mfma_f32_16x16x32_bf16 v[94:97], v[180:183], v[204:207], v[94:97]
	v_mfma_f32_16x16x32_bf16 v[86:89], v[154:157], v[212:215], v[86:89]
	v_mfma_f32_16x16x32_bf16 v[78:81], v[180:183], v[212:215], v[78:81]
	s_barrier
	s_add_i32 s22, 0, 0x1c000
	s_add_i32 s23, s51, s28
	v_add_u32_e32 v175, s22, v147
	v_lshl_add_u64 v[144:145], v[144:145], 0, s[70:71]
	s_mov_b32 m0, s23
	ds_read_b128 v[216:219], v175
	ds_read_b128 v[220:223], v175 offset:1024
	ds_read_b128 v[224:227], v175 offset:2048
	ds_read_b128 v[228:231], v175 offset:3072
	global_load_lds_dwordx4 v[144:145], off
	v_lshl_add_u64 v[144:145], v[158:159], 0, s[70:71]
	s_add_i32 m0, s23, 0x2000
	s_nop 0
	global_load_lds_dwordx4 v[144:145], off
	s_barrier
; #define PG8_STAGE(bufoff, gbase, voff) do { _Pragma("unroll") for (int _i = 0; _i < 2; ++_i) \
;         __builtin_amdgcn_global_load_lds((const unsigned*)((const char*)(gbase) + (voff)[_i]), (PG8_LAS unsigned*)(lds + (bufoff) + ldsw + _i * 8192), 16, 0, 0); } while (0)
; #define PG8_LDA(dst, b, h) do { _Pragma("unroll") for (int m = 0; m < 4; ++m) _Pragma("unroll") for (int k = 0; k < 2; ++k) dst[m][k] = *(const PG8_LAS bf16x8*)(lds + PG8_SA(b, h) + aoff + m * 2048 + k * 1024); } while (0)
; #define PG8_MMA(ai, bj, At, Bt) do { __builtin_amdgcn_s_setprio(1); _Pragma("unroll") for (int m = 0; m < 4; ++m) _Pragma("unroll") for (int n = 0; n < 2; ++n) _Pragma("unroll") for (int k = 0; k < 2; ++k) \
;         acc[ai][bj][m][n] = __builtin_amdgcn_mfma_f32_16x16x32_bf16(Bt[n][k], At[m][k], acc[ai][bj][m][n], 0, 0, 0); __builtin_amdgcn_s_setprio(0); } while (0)
; #define PG8_WAIT_V(n) asm volatile("s_waitcnt vmcnt(" #n ")" ::: "memory")
; #define PG8_WAIT_L(n) asm volatile("s_waitcnt lgkmcnt(" #n ")" ::: "memory")
; #define PG8_BAR __builtin_amdgcn_s_barrier()
; #define PG8_SCHED __builtin_amdgcn_sched_barrier(0)
; template <class Epi, class Sched>
; __device__ __forceinline__ void gemm_phase(PG8_LAS unsigned char* lds, const Gemm g, const Sched& S, const Epi& E) {
;     ...
;             PG8_BAR; PG8_WAIT_L(0); PG8_MMA(0, 1, At, B1); PG8_BAR;
;             PG8_LDA(At, 1, 1); PG8_STAGE(PG8_SA(1, 0), a3, voffA);
;             PG8_BAR; PG8_WAIT_L(0); PG8_MMA(1, 0, At, B0); PG8_BAR; PG8_SCHED;
;             PG8_STAGE(PG8_SB(1, 1), b3 + hstep, voffB);
;             PG8_WAIT_V(6); PG8_BAR; PG8_MMA(1, 1, At, B1); PG8_BAR;
;         }
;     __device__ __forceinline__ void operator()(const f32x4 (&acc)[2][2][4][2], const pg8::Unit& u, int wr, int wc, int fr, int fq) const {
;     ...
;         if (u.pn < 6) { base = PR; pitch = PRW; colt = 256 * u.pn; }
;         else if (u.pn < 12) { base = PH; pitch = PHG; colt = 256 * (u.pn - 6); }
;         else { base = PG; pitch = PGL; colt = 256 * (u.pn - 12); }
	s_waitcnt lgkmcnt(0)
	v_mfma_f32_16x16x32_bf16 v[114:117], v[216:219], v[184:187], v[114:117]
	v_mfma_f32_16x16x32_bf16 v[106:109], v[224:227], v[184:187], v[106:109]
	v_mfma_f32_16x16x32_bf16 v[98:101], v[216:219], v[192:195], v[98:101]
	v_mfma_f32_16x16x32_bf16 v[90:93], v[224:227], v[192:195], v[90:93]
	v_mfma_f32_16x16x32_bf16 v[82:85], v[216:219], v[200:203], v[82:85]
	v_mfma_f32_16x16x32_bf16 v[74:77], v[224:227], v[200:203], v[74:77]
	v_mfma_f32_16x16x32_bf16 v[70:73], v[216:219], v[208:211], v[70:73]
	v_mfma_f32_16x16x32_bf16 v[66:69], v[224:227], v[208:211], v[66:69]
	v_mfma_f32_16x16x32_bf16 v[114:117], v[220:223], v[188:191], v[114:117]
	v_mfma_f32_16x16x32_bf16 v[106:109], v[228:231], v[188:191], v[106:109]
	v_mfma_f32_16x16x32_bf16 v[98:101], v[220:223], v[196:199], v[98:101]
	v_mfma_f32_16x16x32_bf16 v[90:93], v[228:231], v[196:199], v[90:93]
	v_mfma_f32_16x16x32_bf16 v[82:85], v[220:223], v[204:207], v[82:85]
	v_mfma_f32_16x16x32_bf16 v[74:77], v[228:231], v[204:207], v[74:77]
	v_mfma_f32_16x16x32_bf16 v[70:73], v[220:223], v[212:215], v[70:73]
	v_mfma_f32_16x16x32_bf16 v[66:69], v[228:231], v[212:215], v[66:69]
	s_mov_b32 m0, s35
	v_lshl_add_u64 v[144:145], v[232:233], 0, s[70:71]
	s_barrier
	ds_read_b128 v[184:187], v149 offset:49152
	ds_read_b128 v[188:191], v149 offset:50176
	ds_read_b128 v[192:195], v149 offset:51200
	ds_read_b128 v[196:199], v149 offset:52224
	ds_read_b128 v[200:203], v149 offset:53248
	ds_read_b128 v[204:207], v149 offset:54272
	ds_read_b128 v[208:211], v149 offset:55296
	ds_read_b128 v[212:215], v149 offset:56320
	global_load_lds_dwordx4 v[144:145], off
	v_lshl_add_u64 v[144:145], v[234:235], 0, s[70:71]
	s_mov_b32 m0, s36
	s_nop 0
	global_load_lds_dwordx4 v[144:145], off
	s_barrier
	s_waitcnt lgkmcnt(0)
	v_mfma_f32_16x16x32_bf16 v[62:65], v[150:153], v[184:187], v[62:65]
	v_mfma_f32_16x16x32_bf16 v[58:61], v[176:179], v[184:187], v[58:61]
	v_mfma_f32_16x16x32_bf16 v[50:53], v[150:153], v[192:195], v[50:53]
	v_mfma_f32_16x16x32_bf16 v[42:45], v[176:179], v[192:195], v[42:45]
	v_mfma_f32_16x16x32_bf16 v[34:37], v[150:153], v[200:203], v[34:37]
	v_mfma_f32_16x16x32_bf16 v[26:29], v[176:179], v[200:203], v[26:29]
	v_mfma_f32_16x16x32_bf16 v[18:21], v[150:153], v[208:211], v[18:21]
	v_mfma_f32_16x16x32_bf16 v[10:13], v[176:179], v[208:211], v[10:13]
	v_mfma_f32_16x16x32_bf16 v[62:65], v[154:157], v[188:191], v[62:65]
	v_mfma_f32_16x16x32_bf16 v[58:61], v[180:183], v[188:191], v[58:61]
	v_mfma_f32_16x16x32_bf16 v[50:53], v[154:157], v[196:199], v[50:53]
	v_mfma_f32_16x16x32_bf16 v[42:45], v[180:183], v[196:199], v[42:45]
	v_mfma_f32_16x16x32_bf16 v[34:37], v[154:157], v[204:207], v[34:37]
	v_mfma_f32_16x16x32_bf16 v[26:29], v[180:183], v[204:207], v[26:29]
	v_mfma_f32_16x16x32_bf16 v[18:21], v[154:157], v[212:215], v[18:21]
	v_mfma_f32_16x16x32_bf16 v[10:13], v[180:183], v[212:215], v[10:13]
	s_barrier
	s_add_u32 s20, s20, 0x40080
	s_addc_u32 s21, s21, 0
	s_add_i32 s22, s22, s28
	v_lshl_add_u64 v[144:145], s[20:21], 0, v[0:1]
	s_mov_b32 m0, s22
	s_nop 0
	global_load_lds_dwordx4 v[144:145], off
	v_lshl_add_u64 v[144:145], s[20:21], 0, v[134:135]
	s_add_i32 m0, s22, 0x2000
	s_nop 0
	global_load_lds_dwordx4 v[144:145], off
	s_waitcnt vmcnt(6)
	s_barrier
	v_mfma_f32_16x16x32_bf16 v[54:57], v[216:219], v[184:187], v[54:57]
	v_mfma_f32_16x16x32_bf16 v[46:49], v[224:227], v[184:187], v[46:49]
	v_mfma_f32_16x16x32_bf16 v[38:41], v[216:219], v[192:195], v[38:41]
	v_mfma_f32_16x16x32_bf16 v[30:33], v[224:227], v[192:195], v[30:33]
	v_mfma_f32_16x16x32_bf16 v[22:25], v[216:219], v[200:203], v[22:25]
	v_mfma_f32_16x16x32_bf16 v[14:17], v[224:227], v[200:203], v[14:17]
	v_mfma_f32_16x16x32_bf16 v[6:9], v[216:219], v[208:211], v[6:9]
	v_mfma_f32_16x16x32_bf16 v[2:5], v[224:227], v[208:211], v[2:5]
	v_mfma_f32_16x16x32_bf16 v[54:57], v[220:223], v[188:191], v[54:57]
	v_mfma_f32_16x16x32_bf16 v[46:49], v[228:231], v[188:191], v[46:49]
	v_mfma_f32_16x16x32_bf16 v[38:41], v[220:223], v[196:199], v[38:41]
	v_mfma_f32_16x16x32_bf16 v[30:33], v[228:231], v[196:199], v[30:33]
	v_mfma_f32_16x16x32_bf16 v[22:25], v[220:223], v[204:207], v[22:25]
	v_mfma_f32_16x16x32_bf16 v[14:17], v[228:231], v[204:207], v[14:17]
	v_mfma_f32_16x16x32_bf16 v[6:9], v[220:223], v[212:215], v[6:9]
	v_mfma_f32_16x16x32_bf16 v[2:5], v[228:231], v[212:215], v[2:5]
	s_add_i32 s50, s50, 2
	s_add_u32 s18, s18, 0x100
	s_addc_u32 s19, s19, 0
	s_add_u32 s44, s44, 0x100
	s_addc_u32 s45, s45, 0
	s_cmp_gt_u32 s50, 13
	s_barrier
	s_cbranch_scc0 .LBB0_1071
	s_cmp_gt_i32 s39, 5
	s_mov_b64 s[22:23], -1
	s_cbranch_scc0 .LBB0_1078
	s_lshl_b32 s13, s39, 8
	s_cmp_gt_u32 s39, 11
	s_mov_b64 s[20:21], -1
	s_cbranch_scc0 .LBB0_1075
	s_add_i32 s11, s13, 0xfffff400
	s_mov_b64 s[20:21], 0

; #define PG8_STAGE(bufoff, gbase, voff) do { _Pragma("unroll") for (int _i = 0; _i < 2; ++_i) \
;         __builtin_amdgcn_global_load_lds((const unsigned*)((const char*)(gbase) + (voff)[_i]), (PG8_LAS unsigned*)(lds + (bufoff) + ldsw + _i * 8192), 16, 0, 0); } while (0)
; #define PG8_LDA(dst, b, h) do { _Pragma("unroll") for (int m = 0; m < 4; ++m) _Pragma("unroll") for (int k = 0; k < 2; ++k) dst[m][k] = *(const PG8_LAS bf16x8*)(lds + PG8_SA(b, h) + aoff + m * 2048 + k * 1024); } while (0)
; #define PG8_LDB(dst, b, h) do { _Pragma("unroll") for (int n = 0; n < 2; ++n) _Pragma("unroll") for (int k = 0; k < 2; ++k) dst[n][k] = *(const PG8_LAS bf16x8*)(lds + PG8_SB(b, h) + boff + n * 2048 + k * 1024); } while (0)
; #define PG8_MMA(ai, bj, At, Bt) do { __builtin_amdgcn_s_setprio(1); _Pragma("unroll") for (int m = 0; m < 4; ++m) _Pragma("unroll") for (int n = 0; n < 2; ++n) _Pragma("unroll") for (int k = 0; k < 2; ++k) \
;         acc[ai][bj][m][n] = __builtin_amdgcn_mfma_f32_16x16x32_bf16(Bt[n][k], At[m][k], acc[ai][bj][m][n], 0, 0, 0); __builtin_amdgcn_s_setprio(0); } while (0)
; #define PG8_WAIT_L(n) asm volatile("s_waitcnt lgkmcnt(" #n ")" ::: "memory")
; #define PG8_BAR __builtin_amdgcn_s_barrier()
; #define PG8_SCHED __builtin_amdgcn_sched_barrier(0)
; template <class Epi, class Sched>
; __device__ __forceinline__ void gemm_phase(PG8_LAS unsigned char* lds, const Gemm g, const Sched& S, const Epi& E) {
;     ...
;             PG8_LDB(B0, 0, 0); PG8_SCHED; PG8_LDA(At, 0, 0); PG8_STAGE(PG8_SA(1, 1), a1 + hstep, voffA);
;             PG8_WAIT_L(8); PG8_BAR; PG8_WAIT_L(0); PG8_MMA(0, 0, At, B0); PG8_BAR; PG8_SCHED;
;             PG8_LDB(B1, 0, 1); PG8_STAGE(PG8_SB(0, 0), b2, voffB);
;             PG8_BAR; PG8_WAIT_L(0); PG8_MMA(0, 1, At, B1); PG8_BAR;
;             PG8_LDA(At, 0, 1); PG8_STAGE(PG8_SA(0, 0), a2, voffA);
;             PG8_BAR; PG8_WAIT_L(0); PG8_MMA(1, 0, At, B0); PG8_BAR; PG8_SCHED;
.LBB0_1106:
	s_add_i32 s41, s12, 2
	s_add_u32 s14, s10, 0x80
	s_addc_u32 s13, s11, 0
	s_add_i32 s44, 0, 0x10000
	v_add_u32_e32 v137, s44, v151
	ds_read_b128 v[144:147], v137
	ds_read_b128 v[154:157], v137 offset:1024
	ds_read_b128 v[176:179], v137 offset:2048
	ds_read_b128 v[180:183], v137 offset:3072
	s_cmp_eq_u32 s31, s12
	s_cselect_b32 s12, s0, s14
	s_cselect_b32 s13, s1, s13
	s_cselect_b32 s15, s7, s40
	s_cselect_b32 s14, s6, s39
	v_lshl_add_u64 v[148:149], s[10:11], 0, v[140:141]
	s_add_i32 m0, s22, 0xc000
	ds_read_b128 v[184:187], v153
	ds_read_b128 v[188:191], v153 offset:1024
	ds_read_b128 v[192:195], v153 offset:2048
	ds_read_b128 v[196:199], v153 offset:3072
	ds_read_b128 v[200:203], v153 offset:4096
	ds_read_b128 v[204:207], v153 offset:5120
	ds_read_b128 v[208:211], v153 offset:6144
	ds_read_b128 v[212:215], v153 offset:7168
	global_load_lds_dwordx4 v[148:149], off
	v_lshl_add_u64 v[148:149], s[10:11], 0, v[142:143]
	s_add_i32 m0, s22, 0xe000
	s_nop 0
	global_load_lds_dwordx4 v[148:149], off
	s_waitcnt lgkmcnt(8)
	s_barrier
	s_waitcnt lgkmcnt(0)
	v_mfma_f32_16x16x32_bf16 v[126:129], v[144:147], v[184:187], v[126:129]
	v_mfma_f32_16x16x32_bf16 v[122:125], v[176:179], v[184:187], v[122:125]
	v_mfma_f32_16x16x32_bf16 v[110:113], v[144:147], v[192:195], v[110:113]
	v_mfma_f32_16x16x32_bf16 v[106:109], v[176:179], v[192:195], v[106:109]
	v_mfma_f32_16x16x32_bf16 v[94:97], v[144:147], v[200:203], v[94:97]
	v_mfma_f32_16x16x32_bf16 v[90:93], v[176:179], v[200:203], v[90:93]
	v_mfma_f32_16x16x32_bf16 v[78:81], v[144:147], v[208:211], v[78:81]
	v_mfma_f32_16x16x32_bf16 v[74:77], v[176:179], v[208:211], v[74:77]
	v_mfma_f32_16x16x32_bf16 v[126:129], v[154:157], v[188:191], v[126:129]
	v_mfma_f32_16x16x32_bf16 v[122:125], v[180:183], v[188:191], v[122:125]
	v_mfma_f32_16x16x32_bf16 v[110:113], v[154:157], v[196:199], v[110:113]
	v_mfma_f32_16x16x32_bf16 v[106:109], v[180:183], v[196:199], v[106:109]
	v_mfma_f32_16x16x32_bf16 v[94:97], v[154:157], v[204:207], v[94:97]
	v_mfma_f32_16x16x32_bf16 v[90:93], v[180:183], v[204:207], v[90:93]
	v_mfma_f32_16x16x32_bf16 v[78:81], v[154:157], v[212:215], v[78:81]
	v_mfma_f32_16x16x32_bf16 v[74:77], v[180:183], v[212:215], v[74:77]
	s_barrier
	s_add_i32 s45, 0, 0x14000
	s_add_i32 s44, s44, s17
	v_add_u32_e32 v137, s45, v151
	v_lshl_add_u64 v[148:149], s[14:15], 0, v[0:1]
	s_mov_b32 m0, s44
	ds_read_b128 v[216:219], v137
	ds_read_b128 v[220:223], v137 offset:1024
	ds_read_b128 v[224:227], v137 offset:2048
	ds_read_b128 v[228:231], v137 offset:3072
	global_load_lds_dwordx4 v[148:149], off
	v_lshl_add_u64 v[158:159], s[14:15], 0, v[134:135]
	s_add_i32 m0, s44, 0x2000
	s_nop 0
	global_load_lds_dwordx4 v[158:159], off
	s_barrier
	s_waitcnt lgkmcnt(0)
	v_mfma_f32_16x16x32_bf16 v[118:121], v[216:219], v[184:187], v[118:121]
	v_mfma_f32_16x16x32_bf16 v[114:117], v[224:227], v[184:187], v[114:117]
	v_mfma_f32_16x16x32_bf16 v[102:105], v[216:219], v[192:195], v[102:105]
	v_mfma_f32_16x16x32_bf16 v[98:101], v[224:227], v[192:195], v[98:101]
	v_mfma_f32_16x16x32_bf16 v[86:89], v[216:219], v[200:203], v[86:89]
	v_mfma_f32_16x16x32_bf16 v[82:85], v[224:227], v[200:203], v[82:85]
	v_mfma_f32_16x16x32_bf16 v[70:73], v[216:219], v[208:211], v[70:73]
	v_mfma_f32_16x16x32_bf16 v[66:69], v[224:227], v[208:211], v[66:69]
	v_mfma_f32_16x16x32_bf16 v[118:121], v[220:223], v[188:191], v[118:121]
	v_mfma_f32_16x16x32_bf16 v[114:117], v[228:231], v[188:191], v[114:117]
	v_mfma_f32_16x16x32_bf16 v[102:105], v[220:223], v[196:199], v[102:105]
	v_mfma_f32_16x16x32_bf16 v[98:101], v[228:231], v[196:199], v[98:101]
	v_mfma_f32_16x16x32_bf16 v[86:89], v[220:223], v[204:207], v[86:89]
	v_mfma_f32_16x16x32_bf16 v[82:85], v[228:231], v[204:207], v[82:85]
	v_mfma_f32_16x16x32_bf16 v[70:73], v[220:223], v[212:215], v[70:73]
	v_mfma_f32_16x16x32_bf16 v[66:69], v[228:231], v[212:215], v[66:69]
	s_mov_b32 m0, s22
	v_lshl_add_u64 v[232:233], s[12:13], 0, v[0:1]
	s_barrier
	ds_read_b128 v[184:187], v153 offset:16384
	ds_read_b128 v[188:191], v153 offset:17408
	ds_read_b128 v[192:195], v153 offset:18432
	ds_read_b128 v[196:199], v153 offset:19456
	ds_read_b128 v[200:203], v153 offset:20480
	ds_read_b128 v[204:207], v153 offset:21504
	ds_read_b128 v[208:211], v153 offset:22528
	ds_read_b128 v[212:215], v153 offset:23552
	global_load_lds_dwordx4 v[232:233], off
	v_lshl_add_u64 v[234:235], s[12:13], 0, v[134:135]
	s_mov_b32 m0, s23
	s_nop 0
	global_load_lds_dwordx4 v[234:235], off
	s_barrier
	s_waitcnt lgkmcnt(0)
	v_mfma_f32_16x16x32_bf16 v[62:65], v[144:147], v[184:187], v[62:65]
	v_mfma_f32_16x16x32_bf16 v[58:61], v[176:179], v[184:187], v[58:61]
	v_mfma_f32_16x16x32_bf16 v[46:49], v[144:147], v[192:195], v[46:49]
	v_mfma_f32_16x16x32_bf16 v[42:45], v[176:179], v[192:195], v[42:45]
	v_mfma_f32_16x16x32_bf16 v[30:33], v[144:147], v[200:203], v[30:33]
	v_mfma_f32_16x16x32_bf16 v[26:29], v[176:179], v[200:203], v[26:29]
	v_mfma_f32_16x16x32_bf16 v[14:17], v[144:147], v[208:211], v[14:17]
	v_mfma_f32_16x16x32_bf16 v[10:13], v[176:179], v[208:211], v[10:13]
	v_mfma_f32_16x16x32_bf16 v[62:65], v[154:157], v[188:191], v[62:65]
	v_mfma_f32_16x16x32_bf16 v[58:61], v[180:183], v[188:191], v[58:61]
	v_mfma_f32_16x16x32_bf16 v[46:49], v[154:157], v[196:199], v[46:49]
	v_mfma_f32_16x16x32_bf16 v[42:45], v[180:183], v[196:199], v[42:45]
	v_mfma_f32_16x16x32_bf16 v[30:33], v[154:157], v[204:207], v[30:33]
	v_mfma_f32_16x16x32_bf16 v[26:29], v[180:183], v[204:207], v[26:29]
	v_mfma_f32_16x16x32_bf16 v[14:17], v[154:157], v[212:215], v[14:17]
	v_mfma_f32_16x16x32_bf16 v[10:13], v[180:183], v[212:215], v[10:13]
	s_barrier
; #define PG8_STAGE(bufoff, gbase, voff) do { _Pragma("unroll") for (int _i = 0; _i < 2; ++_i) \
;         __builtin_amdgcn_global_load_lds((const unsigned*)((const char*)(gbase) + (voff)[_i]), (PG8_LAS unsigned*)(lds + (bufoff) + ldsw + _i * 8192), 16, 0, 0); } while (0)
; #define PG8_LDA(dst, b, h) do { _Pragma("unroll") for (int m = 0; m < 4; ++m) _Pragma("unroll") for (int k = 0; k < 2; ++k) dst[m][k] = *(const PG8_LAS bf16x8*)(lds + PG8_SA(b, h) + aoff + m * 2048 + k * 1024); } while (0)
; #define PG8_LDB(dst, b, h) do { _Pragma("unroll") for (int n = 0; n < 2; ++n) _Pragma("unroll") for (int k = 0; k < 2; ++k) dst[n][k] = *(const PG8_LAS bf16x8*)(lds + PG8_SB(b, h) + boff + n * 2048 + k * 1024); } while (0)
; #define PG8_MMA(ai, bj, At, Bt) do { __builtin_amdgcn_s_setprio(1); _Pragma("unroll") for (int m = 0; m < 4; ++m) _Pragma("unroll") for (int n = 0; n < 2; ++n) _Pragma("unroll") for (int k = 0; k < 2; ++k) \
;         acc[ai][bj][m][n] = __builtin_amdgcn_mfma_f32_16x16x32_bf16(Bt[n][k], At[m][k], acc[ai][bj][m][n], 0, 0, 0); __builtin_amdgcn_s_setprio(0); } while (0)
; #define PG8_WAIT_V(n) asm volatile("s_waitcnt vmcnt(" #n ")" ::: "memory")
; #define PG8_WAIT_L(n) asm volatile("s_waitcnt lgkmcnt(" #n ")" ::: "memory")
; #define PG8_BAR __builtin_amdgcn_s_barrier()
; #define PG8_SCHED __builtin_amdgcn_sched_barrier(0)
; template <class Epi, class Sched>
; __device__ __forceinline__ void gemm_phase(PG8_LAS unsigned char* lds, const Gemm g, const Sched& S, const Epi& E) {
;     ...
;             PG8_STAGE(PG8_SB(0, 1), b2 + hstep, voffB);
;             PG8_WAIT_V(6); PG8_BAR; PG8_MMA(1, 1, At, B1); PG8_BAR;
;             PG8_LDB(B0, 1, 0); PG8_SCHED; PG8_LDA(At, 1, 0); PG8_STAGE(PG8_SA(0, 1), a2 + hstep, voffA);
;             PG8_WAIT_L(8); PG8_BAR; PG8_WAIT_L(0); PG8_MMA(0, 0, At, B0); PG8_BAR; PG8_SCHED;
;             PG8_LDB(B1, 1, 1); PG8_STAGE(PG8_SB(1, 0), b3, voffB);
;             PG8_BAR; PG8_WAIT_L(0); PG8_MMA(0, 1, At, B1); PG8_BAR;
;             PG8_LDA(At, 1, 1); PG8_STAGE(PG8_SA(1, 0), a3, voffA);
	s_add_u32 s14, s14, s72
	s_addc_u32 s15, s15, 0
	s_add_i32 s44, s45, s17
	v_lshl_add_u64 v[236:237], s[14:15], 0, v[0:1]
	s_mov_b32 m0, s44
	v_lshl_add_u64 v[238:239], s[14:15], 0, v[134:135]
	global_load_lds_dwordx4 v[236:237], off
	s_add_i32 m0, s44, 0x2000
	s_nop 0
	global_load_lds_dwordx4 v[238:239], off
	s_waitcnt vmcnt(6)
	s_barrier
	v_mfma_f32_16x16x32_bf16 v[54:57], v[216:219], v[184:187], v[54:57]
	v_mfma_f32_16x16x32_bf16 v[50:53], v[224:227], v[184:187], v[50:53]
	v_mfma_f32_16x16x32_bf16 v[38:41], v[216:219], v[192:195], v[38:41]
	v_mfma_f32_16x16x32_bf16 v[34:37], v[224:227], v[192:195], v[34:37]
	v_mfma_f32_16x16x32_bf16 v[22:25], v[216:219], v[200:203], v[22:25]
	v_mfma_f32_16x16x32_bf16 v[18:21], v[224:227], v[200:203], v[18:21]
	v_mfma_f32_16x16x32_bf16 v[6:9], v[216:219], v[208:211], v[6:9]
	v_mfma_f32_16x16x32_bf16 v[2:5], v[224:227], v[208:211], v[2:5]
	v_mfma_f32_16x16x32_bf16 v[54:57], v[220:223], v[188:191], v[54:57]
	v_mfma_f32_16x16x32_bf16 v[50:53], v[228:231], v[188:191], v[50:53]
	v_mfma_f32_16x16x32_bf16 v[38:41], v[220:223], v[196:199], v[38:41]
	v_mfma_f32_16x16x32_bf16 v[34:37], v[228:231], v[196:199], v[34:37]
	v_mfma_f32_16x16x32_bf16 v[22:25], v[220:223], v[204:207], v[22:25]
	v_mfma_f32_16x16x32_bf16 v[18:21], v[228:231], v[204:207], v[18:21]
	v_mfma_f32_16x16x32_bf16 v[6:9], v[220:223], v[212:215], v[6:9]
	v_mfma_f32_16x16x32_bf16 v[2:5], v[228:231], v[212:215], v[2:5]
	s_add_i32 s14, 0, 0x18000
	v_add_u32_e32 v137, s14, v151
	s_barrier
	ds_read_b128 v[144:147], v137
	ds_read_b128 v[154:157], v137 offset:1024
	ds_read_b128 v[176:179], v137 offset:2048
	ds_read_b128 v[180:183], v137 offset:3072
	s_add_u32 s12, s12, s72
	s_addc_u32 s13, s13, 0
	s_mov_b32 m0, s26
	v_lshl_add_u64 v[216:217], s[12:13], 0, v[0:1]
	ds_read_b128 v[184:187], v153 offset:32768
	ds_read_b128 v[188:191], v153 offset:33792
	ds_read_b128 v[192:195], v153 offset:34816
	ds_read_b128 v[196:199], v153 offset:35840
	ds_read_b128 v[200:203], v153 offset:36864
	ds_read_b128 v[204:207], v153 offset:37888
	ds_read_b128 v[208:211], v153 offset:38912
	ds_read_b128 v[212:215], v153 offset:39936
	global_load_lds_dwordx4 v[216:217], off
	v_lshl_add_u64 v[216:217], s[12:13], 0, v[134:135]
	s_mov_b32 m0, s27
	s_nop 0
	global_load_lds_dwordx4 v[216:217], off
	s_waitcnt lgkmcnt(8)
	s_barrier
	s_waitcnt lgkmcnt(0)
	v_mfma_f32_16x16x32_bf16 v[126:129], v[144:147], v[184:187], v[126:129]
	v_mfma_f32_16x16x32_bf16 v[122:125], v[176:179], v[184:187], v[122:125]
	v_mfma_f32_16x16x32_bf16 v[110:113], v[144:147], v[192:195], v[110:113]
	v_mfma_f32_16x16x32_bf16 v[106:109], v[176:179], v[192:195], v[106:109]
	v_mfma_f32_16x16x32_bf16 v[94:97], v[144:147], v[200:203], v[94:97]
	v_mfma_f32_16x16x32_bf16 v[90:93], v[176:179], v[200:203], v[90:93]
	v_mfma_f32_16x16x32_bf16 v[78:81], v[144:147], v[208:211], v[78:81]
	v_mfma_f32_16x16x32_bf16 v[74:77], v[176:179], v[208:211], v[74:77]
	v_mfma_f32_16x16x32_bf16 v[126:129], v[154:157], v[188:191], v[126:129]
	v_mfma_f32_16x16x32_bf16 v[122:125], v[180:183], v[188:191], v[122:125]
	v_mfma_f32_16x16x32_bf16 v[110:113], v[154:157], v[196:199], v[110:113]
	v_mfma_f32_16x16x32_bf16 v[106:109], v[180:183], v[196:199], v[106:109]
	v_mfma_f32_16x16x32_bf16 v[94:97], v[154:157], v[204:207], v[94:97]
	v_mfma_f32_16x16x32_bf16 v[90:93], v[180:183], v[204:207], v[90:93]
	v_mfma_f32_16x16x32_bf16 v[78:81], v[154:157], v[212:215], v[78:81]
	v_mfma_f32_16x16x32_bf16 v[74:77], v[180:183], v[212:215], v[74:77]
	s_barrier
	s_add_i32 s12, 0, 0x1c000
	s_add_i32 s13, s14, s17
	v_add_u32_e32 v137, s12, v151
	v_lshl_add_u64 v[148:149], v[148:149], 0, s[70:71]
	s_mov_b32 m0, s13
	ds_read_b128 v[216:219], v137
	ds_read_b128 v[220:223], v137 offset:1024
	ds_read_b128 v[224:227], v137 offset:2048
	ds_read_b128 v[228:231], v137 offset:3072
	global_load_lds_dwordx4 v[148:149], off
	v_lshl_add_u64 v[148:149], v[158:159], 0, s[70:71]
	s_add_i32 m0, s13, 0x2000
	s_nop 0
	global_load_lds_dwordx4 v[148:149], off
	s_barrier
	s_waitcnt lgkmcnt(0)
	v_mfma_f32_16x16x32_bf16 v[118:121], v[216:219], v[184:187], v[118:121]
	v_mfma_f32_16x16x32_bf16 v[114:117], v[224:227], v[184:187], v[114:117]
	v_mfma_f32_16x16x32_bf16 v[102:105], v[216:219], v[192:195], v[102:105]
	v_mfma_f32_16x16x32_bf16 v[98:101], v[224:227], v[192:195], v[98:101]
	v_mfma_f32_16x16x32_bf16 v[86:89], v[216:219], v[200:203], v[86:89]
	v_mfma_f32_16x16x32_bf16 v[82:85], v[224:227], v[200:203], v[82:85]
	v_mfma_f32_16x16x32_bf16 v[70:73], v[216:219], v[208:211], v[70:73]
	v_mfma_f32_16x16x32_bf16 v[66:69], v[224:227], v[208:211], v[66:69]
	v_mfma_f32_16x16x32_bf16 v[118:121], v[220:223], v[188:191], v[118:121]
	v_mfma_f32_16x16x32_bf16 v[114:117], v[228:231], v[188:191], v[114:117]
	v_mfma_f32_16x16x32_bf16 v[102:105], v[220:223], v[196:199], v[102:105]
	v_mfma_f32_16x16x32_bf16 v[98:101], v[228:231], v[196:199], v[98:101]
	v_mfma_f32_16x16x32_bf16 v[86:89], v[220:223], v[204:207], v[86:89]
	v_mfma_f32_16x16x32_bf16 v[82:85], v[228:231], v[204:207], v[82:85]
	v_mfma_f32_16x16x32_bf16 v[70:73], v[220:223], v[212:215], v[70:73]
	v_mfma_f32_16x16x32_bf16 v[66:69], v[228:231], v[212:215], v[66:69]
	s_mov_b32 m0, s28
	v_lshl_add_u64 v[148:149], v[232:233], 0, s[70:71]
	s_barrier
	ds_read_b128 v[184:187], v153 offset:49152
	ds_read_b128 v[188:191], v153 offset:50176
	ds_read_b128 v[192:195], v153 offset:51200
	ds_read_b128 v[196:199], v153 offset:52224
	ds_read_b128 v[200:203], v153 offset:53248
	ds_read_b128 v[204:207], v153 offset:54272
	ds_read_b128 v[208:211], v153 offset:55296
	ds_read_b128 v[212:215], v153 offset:56320
	global_load_lds_dwordx4 v[148:149], off
	v_lshl_add_u64 v[148:149], v[234:235], 0, s[70:71]
	s_mov_b32 m0, s29
	s_nop 0
	global_load_lds_dwordx4 v[148:149], off
	s_barrier
; #define PG8_STAGE(bufoff, gbase, voff) do { _Pragma("unroll") for (int _i = 0; _i < 2; ++_i) \
;         __builtin_amdgcn_global_load_lds((const unsigned*)((const char*)(gbase) + (voff)[_i]), (PG8_LAS unsigned*)(lds + (bufoff) + ldsw + _i * 8192), 16, 0, 0); } while (0)
; #define PG8_MMA(ai, bj, At, Bt) do { __builtin_amdgcn_s_setprio(1); _Pragma("unroll") for (int m = 0; m < 4; ++m) _Pragma("unroll") for (int n = 0; n < 2; ++n) _Pragma("unroll") for (int k = 0; k < 2; ++k) \
;         acc[ai][bj][m][n] = __builtin_amdgcn_mfma_f32_16x16x32_bf16(Bt[n][k], At[m][k], acc[ai][bj][m][n], 0, 0, 0); __builtin_amdgcn_s_setprio(0); } while (0)
; #define PG8_WAIT_V(n) asm volatile("s_waitcnt vmcnt(" #n ")" ::: "memory")
; #define PG8_WAIT_L(n) asm volatile("s_waitcnt lgkmcnt(" #n ")" ::: "memory")
; #define PG8_BAR __builtin_amdgcn_s_barrier()
; #define PG8_SCHED __builtin_amdgcn_sched_barrier(0)
; template <class Epi, class Sched>
; __device__ __forceinline__ void gemm_phase(PG8_LAS unsigned char* lds, const Gemm g, const Sched& S, const Epi& E) {
;     ...
;             PG8_BAR; PG8_WAIT_L(0); PG8_MMA(1, 0, At, B0); PG8_BAR; PG8_SCHED;
;             PG8_STAGE(PG8_SB(1, 1), b3 + hstep, voffB);
;             PG8_WAIT_V(6); PG8_BAR; PG8_MMA(1, 1, At, B1); PG8_BAR;
;         }
;         if constexpr (!Epi::AFTER_DRAIN) { E(acc, cur, wr, wc, fr, fq); S.done(cur); }
;     __device__ __forceinline__ void operator()(const f32x4 (&acc)[2][2][4][2], const pg8::Unit& u, int wr, int wc, int fr, int fq) const {
;         const int row0 = u.pm * 256 + wr * 64 + fr, col0 = u.pn * 256 + wc * 32 + 4 * fq;
; #pragma unroll
;         for (int ai = 0; ai < 2; ++ai)
; #pragma unroll
;             for (int m = 0; m < 4; ++m) {
;                 const size_t ro = (size_t)(row0 + ai * 128 + m * 16) * D + col0;
; #pragma unroll
;                 for (int bj = 0; bj < 2; ++bj)
; #pragma unroll
;                     for (int n = 0; n < 2; ++n) { const size_t o = ro + bj * 128 + n * 16; *(f32x4*)(X + o) = *(const f32x4*)(Xs + o) + acc[ai][bj][m][n] * scale; }
;             }
	s_waitcnt lgkmcnt(0)
	v_mfma_f32_16x16x32_bf16 v[62:65], v[144:147], v[184:187], v[62:65]
	v_mfma_f32_16x16x32_bf16 v[58:61], v[176:179], v[184:187], v[58:61]
	v_mfma_f32_16x16x32_bf16 v[46:49], v[144:147], v[192:195], v[46:49]
	v_mfma_f32_16x16x32_bf16 v[42:45], v[176:179], v[192:195], v[42:45]
	v_mfma_f32_16x16x32_bf16 v[30:33], v[144:147], v[200:203], v[30:33]
	v_mfma_f32_16x16x32_bf16 v[26:29], v[176:179], v[200:203], v[26:29]
	v_mfma_f32_16x16x32_bf16 v[14:17], v[144:147], v[208:211], v[14:17]
	v_mfma_f32_16x16x32_bf16 v[10:13], v[176:179], v[208:211], v[10:13]
	v_mfma_f32_16x16x32_bf16 v[62:65], v[154:157], v[188:191], v[62:65]
	v_mfma_f32_16x16x32_bf16 v[58:61], v[180:183], v[188:191], v[58:61]
	v_mfma_f32_16x16x32_bf16 v[46:49], v[154:157], v[196:199], v[46:49]
	v_mfma_f32_16x16x32_bf16 v[42:45], v[180:183], v[196:199], v[42:45]
	v_mfma_f32_16x16x32_bf16 v[30:33], v[154:157], v[204:207], v[30:33]
	v_mfma_f32_16x16x32_bf16 v[26:29], v[180:183], v[204:207], v[26:29]
	v_mfma_f32_16x16x32_bf16 v[14:17], v[154:157], v[212:215], v[14:17]
	v_mfma_f32_16x16x32_bf16 v[10:13], v[180:183], v[212:215], v[10:13]
	s_barrier
	s_add_i32 s12, s12, s17
	v_lshl_add_u64 v[144:145], v[236:237], 0, s[70:71]
	s_mov_b32 m0, s12
	s_nop 0
	global_load_lds_dwordx4 v[144:145], off
	v_lshl_add_u64 v[144:145], v[238:239], 0, s[70:71]
	s_add_i32 m0, s12, 0x2000
	s_nop 0
	global_load_lds_dwordx4 v[144:145], off
	s_waitcnt vmcnt(6)
	s_barrier
	v_mfma_f32_16x16x32_bf16 v[54:57], v[216:219], v[184:187], v[54:57]
	v_mfma_f32_16x16x32_bf16 v[50:53], v[224:227], v[184:187], v[50:53]
	v_mfma_f32_16x16x32_bf16 v[38:41], v[216:219], v[192:195], v[38:41]
	v_mfma_f32_16x16x32_bf16 v[34:37], v[224:227], v[192:195], v[34:37]
	v_mfma_f32_16x16x32_bf16 v[22:25], v[216:219], v[200:203], v[22:25]
	v_mfma_f32_16x16x32_bf16 v[18:21], v[224:227], v[200:203], v[18:21]
	v_mfma_f32_16x16x32_bf16 v[6:9], v[216:219], v[208:211], v[6:9]
	v_mfma_f32_16x16x32_bf16 v[2:5], v[224:227], v[208:211], v[2:5]
	v_mfma_f32_16x16x32_bf16 v[54:57], v[220:223], v[188:191], v[54:57]
	v_mfma_f32_16x16x32_bf16 v[50:53], v[228:231], v[188:191], v[50:53]
	v_mfma_f32_16x16x32_bf16 v[38:41], v[220:223], v[196:199], v[38:41]
	v_mfma_f32_16x16x32_bf16 v[34:37], v[228:231], v[196:199], v[34:37]
	v_mfma_f32_16x16x32_bf16 v[22:25], v[220:223], v[204:207], v[22:25]
	v_mfma_f32_16x16x32_bf16 v[18:21], v[228:231], v[204:207], v[18:21]
	v_mfma_f32_16x16x32_bf16 v[6:9], v[220:223], v[212:215], v[6:9]
	v_mfma_f32_16x16x32_bf16 v[2:5], v[228:231], v[212:215], v[2:5]
	s_add_u32 s10, s10, 0x100
	s_addc_u32 s11, s11, 0
	s_add_u32 s39, s39, 0x100
	s_addc_u32 s40, s40, 0
	s_cmp_ge_u32 s41, s30
	s_mov_b32 s12, s41
	s_barrier
	s_cbranch_scc0 .LBB0_1106
	v_lshl_add_u32 v148, s38, 8, v150
	v_lshl_or_b32 v146, s37, 8, v152
	v_lshl_add_u32 v208, v148, 10, v146
	v_mov_b32_e32 v137, v136
	s_and_b64 vcc, exec, s[4:5]
	s_mov_b32 s37, s35
	s_mov_b32 s38, s36
	s_mov_b64 s[12:13], s[6:7]
	s_mov_b64 s[10:11], s[0:1]
	v_lshlrev_b32_e32 v208, 2, v208
	v_add_u32_e32 v209, 0x10000, v208
	v_add_u32_e32 v210, 0x20000, v208
	v_add_u32_e32 v211, 0x30000, v208
	v_add_u32_e32 v212, 0x80000, v208
	v_add_u32_e32 v213, 0x90000, v208
	v_add_u32_e32 v214, 0xa0000, v208
	v_add_u32_e32 v215, 0xb0000, v208
	global_load_dwordx4 v[176:179], v208, s[8:9]
	global_load_dwordx4 v[180:183], v208, s[8:9] offset:64
	global_load_dwordx4 v[184:187], v208, s[8:9] offset:512
	global_load_dwordx4 v[188:191], v208, s[8:9] offset:576
	global_load_dwordx4 v[192:195], v209, s[8:9]
	global_load_dwordx4 v[196:199], v209, s[8:9] offset:64
	global_load_dwordx4 v[200:203], v209, s[8:9] offset:512
	global_load_dwordx4 v[204:207], v209, s[8:9] offset:576
	s_waitcnt vmcnt(7)
	v_pk_fma_f32 v[128:129], v[136:137], v[128:129], v[178:179]
	v_pk_fma_f32 v[126:127], v[138:139], v[126:127], v[176:177]
	global_store_dwordx4 v208, v[126:129], s[92:93]
	s_waitcnt vmcnt(7)
	v_pk_fma_f32 v[124:125], v[136:137], v[124:125], v[182:183]
	v_pk_fma_f32 v[122:123], v[138:139], v[122:123], v[180:181]
	global_store_dwordx4 v208, v[122:125], s[92:93] offset:64
	s_waitcnt vmcnt(7)
	v_pk_fma_f32 v[120:121], v[136:137], v[120:121], v[186:187]
	v_pk_fma_f32 v[118:119], v[138:139], v[118:119], v[184:185]
	global_store_dwordx4 v208, v[118:121], s[92:93] offset:512
	s_waitcnt vmcnt(7)
	v_pk_fma_f32 v[116:117], v[136:137], v[116:117], v[190:191]
	v_pk_fma_f32 v[114:115], v[138:139], v[114:115], v[188:189]
	global_store_dwordx4 v208, v[114:117], s[92:93] offset:576
	global_load_dwordx4 v[176:179], v210, s[8:9]
	global_load_dwordx4 v[180:183], v210, s[8:9] offset:64
	global_load_dwordx4 v[184:187], v210, s[8:9] offset:512
	global_load_dwordx4 v[188:191], v210, s[8:9] offset:576
	s_waitcnt vmcnt(11)
	v_pk_fma_f32 v[112:113], v[136:137], v[112:113], v[194:195]
	v_pk_fma_f32 v[110:111], v[138:139], v[110:111], v[192:193]
	global_store_dwordx4 v209, v[110:113], s[92:93]
	s_waitcnt vmcnt(11)
	v_pk_fma_f32 v[108:109], v[136:137], v[108:109], v[198:199]
	v_pk_fma_f32 v[106:107], v[138:139], v[106:107], v[196:197]
	global_store_dwordx4 v209, v[106:109], s[92:93] offset:64
	s_waitcnt vmcnt(11)
	v_pk_fma_f32 v[104:105], v[136:137], v[104:105], v[202:203]
	v_pk_fma_f32 v[102:103], v[138:139], v[102:103], v[200:201]
	global_store_dwordx4 v209, v[102:105], s[92:93] offset:512
	s_waitcnt vmcnt(11)
	v_pk_fma_f32 v[100:101], v[136:137], v[100:101], v[206:207]
	v_pk_fma_f32 v[98:99], v[138:139], v[98:99], v[204:205]
	global_store_dwordx4 v209, v[98:101], s[92:93] offset:576
	global_load_dwordx4 v[192:195], v211, s[8:9]
	global_load_dwordx4 v[196:199], v211, s[8:9] offset:64
	global_load_dwordx4 v[200:203], v211, s[8:9] offset:512
	global_load_dwordx4 v[204:207], v211, s[8:9] offset:576
	s_waitcnt vmcnt(11)
; #define PG8_WAIT_V(n) asm volatile("s_waitcnt vmcnt(" #n ")" ::: "memory")
; #define PG8_BAR __builtin_amdgcn_s_barrier()
; template <class Epi, class Sched>
; __device__ __forceinline__ void gemm_phase(PG8_LAS unsigned char* lds, const Gemm g, const Sched& S, const Epi& E) {
;     ...
;         if (!has_next) break;
; #pragma unroll
;         for (int a = 0; a < 2; ++a)
; #pragma unroll
;             for (int b = 0; b < 2; ++b)
; #pragma unroll
;                 for (int m = 0; m < 4; ++m)
; #pragma unroll
;                     for (int n = 0; n < 2; ++n) acc[a][b][m][n] = (f32x4){0.f, 0.f, 0.f, 0.f};
;         cur = nxt; cA = nA; cB = nB; ++ui;
;     }
;     PG8_WAIT_V(0);
;     if (wr == 0) PG8_BAR;
;     PG8_BAR;
;     __device__ __forceinline__ void operator()(const f32x4 (&acc)[2][2][4][2], const pg8::Unit& u, int wr, int wc, int fr, int fq) const {
;         const int row0 = u.pm * 256 + wr * 64 + fr, col0 = u.pn * 256 + wc * 32 + 4 * fq;
; #pragma unroll
;         for (int ai = 0; ai < 2; ++ai)
; #pragma unroll
;             for (int m = 0; m < 4; ++m) {
;                 const size_t ro = (size_t)(row0 + ai * 128 + m * 16) * D + col0;
; #pragma unroll
;                 for (int bj = 0; bj < 2; ++bj)
; #pragma unroll
;                     for (int n = 0; n < 2; ++n) { const size_t o = ro + bj * 128 + n * 16; *(f32x4*)(X + o) = *(const f32x4*)(Xs + o) + acc[ai][bj][m][n] * scale; }
;             }
	v_pk_fma_f32 v[96:97], v[136:137], v[96:97], v[178:179]
	v_pk_fma_f32 v[94:95], v[138:139], v[94:95], v[176:177]
	global_store_dwordx4 v210, v[94:97], s[92:93]
	s_waitcnt vmcnt(11)
	v_pk_fma_f32 v[92:93], v[136:137], v[92:93], v[182:183]
	v_pk_fma_f32 v[90:91], v[138:139], v[90:91], v[180:181]
	global_store_dwordx4 v210, v[90:93], s[92:93] offset:64
	s_waitcnt vmcnt(11)
	v_pk_fma_f32 v[88:89], v[136:137], v[88:89], v[186:187]
	v_pk_fma_f32 v[86:87], v[138:139], v[86:87], v[184:185]
	global_store_dwordx4 v210, v[86:89], s[92:93] offset:512
	s_waitcnt vmcnt(11)
	v_pk_fma_f32 v[84:85], v[136:137], v[84:85], v[190:191]
	v_pk_fma_f32 v[82:83], v[138:139], v[82:83], v[188:189]
	global_store_dwordx4 v210, v[82:85], s[92:93] offset:576
	global_load_dwordx4 v[176:179], v212, s[8:9]
	global_load_dwordx4 v[180:183], v212, s[8:9] offset:64
	global_load_dwordx4 v[184:187], v212, s[8:9] offset:512
	global_load_dwordx4 v[188:191], v212, s[8:9] offset:576
	s_waitcnt vmcnt(11)
	v_pk_fma_f32 v[80:81], v[136:137], v[80:81], v[194:195]
	v_pk_fma_f32 v[78:79], v[138:139], v[78:79], v[192:193]
	global_store_dwordx4 v211, v[78:81], s[92:93]
	s_waitcnt vmcnt(11)
	v_pk_fma_f32 v[76:77], v[136:137], v[76:77], v[198:199]
	v_pk_fma_f32 v[74:75], v[138:139], v[74:75], v[196:197]
	global_store_dwordx4 v211, v[74:77], s[92:93] offset:64
	s_waitcnt vmcnt(11)
	v_pk_fma_f32 v[72:73], v[136:137], v[72:73], v[202:203]
	v_pk_fma_f32 v[70:71], v[138:139], v[70:71], v[200:201]
	global_store_dwordx4 v211, v[70:73], s[92:93] offset:512
	s_waitcnt vmcnt(11)
	v_pk_fma_f32 v[68:69], v[136:137], v[68:69], v[206:207]
	v_pk_fma_f32 v[66:67], v[138:139], v[66:67], v[204:205]
	global_store_dwordx4 v211, v[66:69], s[92:93] offset:576
	global_load_dwordx4 v[192:195], v213, s[8:9]
	global_load_dwordx4 v[196:199], v213, s[8:9] offset:64
	global_load_dwordx4 v[200:203], v213, s[8:9] offset:512
	global_load_dwordx4 v[204:207], v213, s[8:9] offset:576
	s_waitcnt vmcnt(11)
	v_pk_fma_f32 v[64:65], v[136:137], v[64:65], v[178:179]
	v_pk_fma_f32 v[62:63], v[138:139], v[62:63], v[176:177]
	global_store_dwordx4 v212, v[62:65], s[92:93]
	s_waitcnt vmcnt(11)
	v_pk_fma_f32 v[60:61], v[136:137], v[60:61], v[182:183]
	v_pk_fma_f32 v[58:59], v[138:139], v[58:59], v[180:181]
	global_store_dwordx4 v212, v[58:61], s[92:93] offset:64
	s_waitcnt vmcnt(11)
	v_pk_fma_f32 v[56:57], v[136:137], v[56:57], v[186:187]
	v_pk_fma_f32 v[54:55], v[138:139], v[54:55], v[184:185]
	global_store_dwordx4 v212, v[54:57], s[92:93] offset:512
	s_waitcnt vmcnt(11)
	v_pk_fma_f32 v[52:53], v[136:137], v[52:53], v[190:191]
	v_pk_fma_f32 v[50:51], v[138:139], v[50:51], v[188:189]
	global_store_dwordx4 v212, v[50:53], s[92:93] offset:576
	global_load_dwordx4 v[176:179], v214, s[8:9]
	global_load_dwordx4 v[180:183], v214, s[8:9] offset:64
	global_load_dwordx4 v[184:187], v214, s[8:9] offset:512
	global_load_dwordx4 v[188:191], v214, s[8:9] offset:576
	s_waitcnt vmcnt(11)
	v_pk_fma_f32 v[48:49], v[136:137], v[48:49], v[194:195]
	v_pk_fma_f32 v[46:47], v[138:139], v[46:47], v[192:193]
	global_store_dwordx4 v213, v[46:49], s[92:93]
	s_waitcnt vmcnt(11)
	v_pk_fma_f32 v[44:45], v[136:137], v[44:45], v[198:199]
	v_pk_fma_f32 v[42:43], v[138:139], v[42:43], v[196:197]
	global_store_dwordx4 v213, v[42:45], s[92:93] offset:64
	s_waitcnt vmcnt(11)
	v_pk_fma_f32 v[40:41], v[136:137], v[40:41], v[202:203]
	v_pk_fma_f32 v[38:39], v[138:139], v[38:39], v[200:201]
	global_store_dwordx4 v213, v[38:41], s[92:93] offset:512
	s_waitcnt vmcnt(11)
	v_pk_fma_f32 v[36:37], v[136:137], v[36:37], v[206:207]
	v_pk_fma_f32 v[34:35], v[138:139], v[34:35], v[204:205]
	global_store_dwordx4 v213, v[34:37], s[92:93] offset:576
	global_load_dwordx4 v[192:195], v215, s[8:9]
	global_load_dwordx4 v[196:199], v215, s[8:9] offset:64
	global_load_dwordx4 v[200:203], v215, s[8:9] offset:512
	global_load_dwordx4 v[204:207], v215, s[8:9] offset:576
	s_waitcnt vmcnt(11)
	v_pk_fma_f32 v[32:33], v[136:137], v[32:33], v[178:179]
	v_pk_fma_f32 v[30:31], v[138:139], v[30:31], v[176:177]
	global_store_dwordx4 v214, v[30:33], s[92:93]
	s_waitcnt vmcnt(11)
	v_pk_fma_f32 v[28:29], v[136:137], v[28:29], v[182:183]
	v_pk_fma_f32 v[26:27], v[138:139], v[26:27], v[180:181]
	global_store_dwordx4 v214, v[26:29], s[92:93] offset:64
	s_waitcnt vmcnt(11)
	v_pk_fma_f32 v[24:25], v[136:137], v[24:25], v[186:187]
	v_pk_fma_f32 v[22:23], v[138:139], v[22:23], v[184:185]
	global_store_dwordx4 v214, v[22:25], s[92:93] offset:512
	s_waitcnt vmcnt(11)
	v_pk_fma_f32 v[20:21], v[136:137], v[20:21], v[190:191]
	v_pk_fma_f32 v[18:19], v[138:139], v[18:19], v[188:189]
	global_store_dwordx4 v214, v[18:21], s[92:93] offset:576
	s_waitcnt vmcnt(7)
	v_pk_fma_f32 v[16:17], v[136:137], v[16:17], v[194:195]
	v_pk_fma_f32 v[14:15], v[138:139], v[14:15], v[192:193]
	global_store_dwordx4 v215, v[14:17], s[92:93]
	s_waitcnt vmcnt(7)
	v_pk_fma_f32 v[12:13], v[136:137], v[12:13], v[198:199]
	v_pk_fma_f32 v[10:11], v[138:139], v[10:11], v[196:197]
	global_store_dwordx4 v215, v[10:13], s[92:93] offset:64
	s_waitcnt vmcnt(7)
	v_pk_fma_f32 v[8:9], v[136:137], v[8:9], v[202:203]
	v_pk_fma_f32 v[6:7], v[138:139], v[6:7], v[200:201]
	global_store_dwordx4 v215, v[6:9], s[92:93] offset:512
	s_waitcnt vmcnt(7)
	v_pk_fma_f32 v[4:5], v[136:137], v[4:5], v[206:207]
	v_pk_fma_f32 v[2:3], v[138:139], v[2:3], v[204:205]
	global_store_dwordx4 v215, v[2:5], s[92:93] offset:576
	s_cbranch_vccz .LBB0_1095
	s_waitcnt vmcnt(0)
	s_cmpk_gt_u32 s2, 0xff
	s_cbranch_scc1 .LBB0_1110
	s_barrier

; #define PG8_STAGE(bufoff, gbase, voff) do { _Pragma("unroll") for (int _i = 0; _i < 2; ++_i) \
;         __builtin_amdgcn_global_load_lds((const unsigned*)((const char*)(gbase) + (voff)[_i]), (PG8_LAS unsigned*)(lds + (bufoff) + ldsw + _i * 8192), 16, 0, 0); } while (0)
; #define PG8_LDA(dst, b, h) do { _Pragma("unroll") for (int m = 0; m < 4; ++m) _Pragma("unroll") for (int k = 0; k < 2; ++k) dst[m][k] = *(const PG8_LAS bf16x8*)(lds + PG8_SA(b, h) + aoff + m * 2048 + k * 1024); } while (0)
; #define PG8_LDB(dst, b, h) do { _Pragma("unroll") for (int n = 0; n < 2; ++n) _Pragma("unroll") for (int k = 0; k < 2; ++k) dst[n][k] = *(const PG8_LAS bf16x8*)(lds + PG8_SB(b, h) + boff + n * 2048 + k * 1024); } while (0)
; #define PG8_MMA(ai, bj, At, Bt) do { __builtin_amdgcn_s_setprio(1); _Pragma("unroll") for (int m = 0; m < 4; ++m) _Pragma("unroll") for (int n = 0; n < 2; ++n) _Pragma("unroll") for (int k = 0; k < 2; ++k) \
;         acc[ai][bj][m][n] = __builtin_amdgcn_mfma_f32_16x16x32_bf16(Bt[n][k], At[m][k], acc[ai][bj][m][n], 0, 0, 0); __builtin_amdgcn_s_setprio(0); } while (0)
; #define PG8_WAIT_L(n) asm volatile("s_waitcnt lgkmcnt(" #n ")" ::: "memory")
; #define PG8_BAR __builtin_amdgcn_s_barrier()
; #define PG8_SCHED __builtin_amdgcn_sched_barrier(0)
; template <class Epi, class Sched>
; __device__ __forceinline__ void gemm_phase(PG8_LAS unsigned char* lds, const Gemm g, const Sched& S, const Epi& E) {
;     ...
;             PG8_LDB(B0, 0, 0); PG8_SCHED; PG8_LDA(At, 0, 0); PG8_STAGE(PG8_SA(1, 1), a1 + hstep, voffA);
;             PG8_WAIT_L(8); PG8_BAR; PG8_WAIT_L(0); PG8_MMA(0, 0, At, B0); PG8_BAR; PG8_SCHED;
;             PG8_LDB(B1, 0, 1); PG8_STAGE(PG8_SB(0, 0), b2, voffB);
;             PG8_BAR; PG8_WAIT_L(0); PG8_MMA(0, 1, At, B1); PG8_BAR;
;             PG8_LDA(At, 0, 1); PG8_STAGE(PG8_SA(0, 0), a2, voffA);
;             PG8_BAR; PG8_WAIT_L(0); PG8_MMA(1, 0, At, B0); PG8_BAR; PG8_SCHED;
.LBB0_1129:
	s_add_u32 s16, s14, 0xfffc0080
	s_addc_u32 s17, s15, -1
	s_add_i32 s41, 0, 0x10000
	v_add_u32_e32 v175, s41, v149
	ds_read_b128 v[144:147], v175
	ds_read_b128 v[152:155], v175 offset:1024
	ds_read_b128 v[156:159], v175 offset:2048
	ds_read_b128 v[176:179], v175 offset:3072
	s_cmp_eq_u32 s40, 12
	s_cselect_b32 s19, s9, s17
	s_cselect_b32 s18, s36, s16
	s_cselect_b32 s17, s7, s39
	s_cselect_b32 s16, s37, s38
	v_lshl_add_u64 v[212:213], s[14:15], 0, v[140:141]
	s_add_i32 m0, s25, 0xc000
	ds_read_b128 v[180:183], v151
	ds_read_b128 v[184:187], v151 offset:1024
	ds_read_b128 v[188:191], v151 offset:2048
	ds_read_b128 v[192:195], v151 offset:3072
	ds_read_b128 v[196:199], v151 offset:4096
	ds_read_b128 v[200:203], v151 offset:5120
	ds_read_b128 v[204:207], v151 offset:6144
	ds_read_b128 v[208:211], v151 offset:7168
	global_load_lds_dwordx4 v[212:213], off
	v_lshl_add_u64 v[212:213], s[14:15], 0, v[142:143]
	s_add_i32 m0, s25, 0xe000
	s_nop 0
	global_load_lds_dwordx4 v[212:213], off
	s_waitcnt lgkmcnt(8)
	s_barrier
	s_waitcnt lgkmcnt(0)
	v_mfma_f32_16x16x32_bf16 v[126:129], v[144:147], v[180:183], v[126:129]
	v_mfma_f32_16x16x32_bf16 v[118:121], v[156:159], v[180:183], v[118:121]
	v_mfma_f32_16x16x32_bf16 v[110:113], v[144:147], v[188:191], v[110:113]
	v_mfma_f32_16x16x32_bf16 v[102:105], v[156:159], v[188:191], v[102:105]
	v_mfma_f32_16x16x32_bf16 v[94:97], v[144:147], v[196:199], v[94:97]
	v_mfma_f32_16x16x32_bf16 v[86:89], v[156:159], v[196:199], v[86:89]
	v_mfma_f32_16x16x32_bf16 v[78:81], v[144:147], v[204:207], v[78:81]
	v_mfma_f32_16x16x32_bf16 v[70:73], v[156:159], v[204:207], v[70:73]
	v_mfma_f32_16x16x32_bf16 v[126:129], v[152:155], v[184:187], v[126:129]
	v_mfma_f32_16x16x32_bf16 v[118:121], v[176:179], v[184:187], v[118:121]
	v_mfma_f32_16x16x32_bf16 v[110:113], v[152:155], v[192:195], v[110:113]
	v_mfma_f32_16x16x32_bf16 v[102:105], v[176:179], v[192:195], v[102:105]
	v_mfma_f32_16x16x32_bf16 v[94:97], v[152:155], v[200:203], v[94:97]
	v_mfma_f32_16x16x32_bf16 v[86:89], v[176:179], v[200:203], v[86:89]
	v_mfma_f32_16x16x32_bf16 v[78:81], v[152:155], v[208:211], v[78:81]
	v_mfma_f32_16x16x32_bf16 v[70:73], v[176:179], v[208:211], v[70:73]
	s_barrier
	s_add_i32 s50, 0, 0x14000
	s_add_i32 s41, s41, s24
	v_add_u32_e32 v175, s50, v149
	v_lshl_add_u64 v[228:229], s[16:17], 0, v[0:1]
	s_mov_b32 m0, s41
	ds_read_b128 v[212:215], v175
	ds_read_b128 v[216:219], v175 offset:1024
	ds_read_b128 v[220:223], v175 offset:2048
	ds_read_b128 v[224:227], v175 offset:3072
	global_load_lds_dwordx4 v[228:229], off
	v_lshl_add_u64 v[230:231], s[16:17], 0, v[134:135]
	s_add_i32 m0, s41, 0x2000
	s_nop 0
	global_load_lds_dwordx4 v[230:231], off
	s_barrier
	s_waitcnt lgkmcnt(0)
	v_mfma_f32_16x16x32_bf16 v[122:125], v[212:215], v[180:183], v[122:125]
	v_mfma_f32_16x16x32_bf16 v[114:117], v[220:223], v[180:183], v[114:117]
	v_mfma_f32_16x16x32_bf16 v[106:109], v[212:215], v[188:191], v[106:109]
	v_mfma_f32_16x16x32_bf16 v[98:101], v[220:223], v[188:191], v[98:101]
	v_mfma_f32_16x16x32_bf16 v[90:93], v[212:215], v[196:199], v[90:93]
	v_mfma_f32_16x16x32_bf16 v[82:85], v[220:223], v[196:199], v[82:85]
	v_mfma_f32_16x16x32_bf16 v[74:77], v[212:215], v[204:207], v[74:77]
	v_mfma_f32_16x16x32_bf16 v[66:69], v[220:223], v[204:207], v[66:69]
	v_mfma_f32_16x16x32_bf16 v[122:125], v[216:219], v[184:187], v[122:125]
	v_mfma_f32_16x16x32_bf16 v[114:117], v[224:227], v[184:187], v[114:117]
	v_mfma_f32_16x16x32_bf16 v[106:109], v[216:219], v[192:195], v[106:109]
	v_mfma_f32_16x16x32_bf16 v[98:101], v[224:227], v[192:195], v[98:101]
	v_mfma_f32_16x16x32_bf16 v[90:93], v[216:219], v[200:203], v[90:93]
	v_mfma_f32_16x16x32_bf16 v[82:85], v[224:227], v[200:203], v[82:85]
	v_mfma_f32_16x16x32_bf16 v[74:77], v[216:219], v[208:211], v[74:77]
	v_mfma_f32_16x16x32_bf16 v[66:69], v[224:227], v[208:211], v[66:69]
	s_mov_b32 m0, s25
	v_lshl_add_u64 v[232:233], s[18:19], 0, v[138:139]
	s_barrier
	ds_read_b128 v[180:183], v151 offset:16384
	ds_read_b128 v[184:187], v151 offset:17408
	ds_read_b128 v[188:191], v151 offset:18432
	ds_read_b128 v[192:195], v151 offset:19456
	ds_read_b128 v[196:199], v151 offset:20480
	ds_read_b128 v[200:203], v151 offset:21504
	ds_read_b128 v[204:207], v151 offset:22528
	ds_read_b128 v[208:211], v151 offset:23552
	global_load_lds_dwordx4 v[232:233], off
	v_lshl_add_u64 v[234:235], s[18:19], 0, v[136:137]
	s_mov_b32 m0, s26
	s_nop 0
	global_load_lds_dwordx4 v[234:235], off
	s_barrier
	s_waitcnt lgkmcnt(0)
	v_mfma_f32_16x16x32_bf16 v[62:65], v[144:147], v[180:183], v[62:65]
	v_mfma_f32_16x16x32_bf16 v[54:57], v[156:159], v[180:183], v[54:57]
	v_mfma_f32_16x16x32_bf16 v[46:49], v[144:147], v[188:191], v[46:49]
	v_mfma_f32_16x16x32_bf16 v[38:41], v[156:159], v[188:191], v[38:41]
	v_mfma_f32_16x16x32_bf16 v[30:33], v[144:147], v[196:199], v[30:33]
	v_mfma_f32_16x16x32_bf16 v[22:25], v[156:159], v[196:199], v[22:25]
	v_mfma_f32_16x16x32_bf16 v[14:17], v[144:147], v[204:207], v[14:17]
	v_mfma_f32_16x16x32_bf16 v[6:9], v[156:159], v[204:207], v[6:9]
	v_mfma_f32_16x16x32_bf16 v[62:65], v[152:155], v[184:187], v[62:65]
	v_mfma_f32_16x16x32_bf16 v[54:57], v[176:179], v[184:187], v[54:57]
	v_mfma_f32_16x16x32_bf16 v[46:49], v[152:155], v[192:195], v[46:49]
	v_mfma_f32_16x16x32_bf16 v[38:41], v[176:179], v[192:195], v[38:41]
	v_mfma_f32_16x16x32_bf16 v[30:33], v[152:155], v[200:203], v[30:33]
	v_mfma_f32_16x16x32_bf16 v[22:25], v[176:179], v[200:203], v[22:25]
	v_mfma_f32_16x16x32_bf16 v[14:17], v[152:155], v[208:211], v[14:17]
	v_mfma_f32_16x16x32_bf16 v[6:9], v[176:179], v[208:211], v[6:9]
	s_barrier
; #define PG8_STAGE(bufoff, gbase, voff) do { _Pragma("unroll") for (int _i = 0; _i < 2; ++_i) \
;         __builtin_amdgcn_global_load_lds((const unsigned*)((const char*)(gbase) + (voff)[_i]), (PG8_LAS unsigned*)(lds + (bufoff) + ldsw + _i * 8192), 16, 0, 0); } while (0)
; #define PG8_LDA(dst, b, h) do { _Pragma("unroll") for (int m = 0; m < 4; ++m) _Pragma("unroll") for (int k = 0; k < 2; ++k) dst[m][k] = *(const PG8_LAS bf16x8*)(lds + PG8_SA(b, h) + aoff + m * 2048 + k * 1024); } while (0)
; #define PG8_LDB(dst, b, h) do { _Pragma("unroll") for (int n = 0; n < 2; ++n) _Pragma("unroll") for (int k = 0; k < 2; ++k) dst[n][k] = *(const PG8_LAS bf16x8*)(lds + PG8_SB(b, h) + boff + n * 2048 + k * 1024); } while (0)
; #define PG8_MMA(ai, bj, At, Bt) do { __builtin_amdgcn_s_setprio(1); _Pragma("unroll") for (int m = 0; m < 4; ++m) _Pragma("unroll") for (int n = 0; n < 2; ++n) _Pragma("unroll") for (int k = 0; k < 2; ++k) \
;         acc[ai][bj][m][n] = __builtin_amdgcn_mfma_f32_16x16x32_bf16(Bt[n][k], At[m][k], acc[ai][bj][m][n], 0, 0, 0); __builtin_amdgcn_s_setprio(0); } while (0)
; #define PG8_WAIT_V(n) asm volatile("s_waitcnt vmcnt(" #n ")" ::: "memory")
; #define PG8_WAIT_L(n) asm volatile("s_waitcnt lgkmcnt(" #n ")" ::: "memory")
; #define PG8_BAR __builtin_amdgcn_s_barrier()
; #define PG8_SCHED __builtin_amdgcn_sched_barrier(0)
; template <class Epi, class Sched>
; __device__ __forceinline__ void gemm_phase(PG8_LAS unsigned char* lds, const Gemm g, const Sched& S, const Epi& E) {
;     ...
;             PG8_STAGE(PG8_SB(0, 1), b2 + hstep, voffB);
;             PG8_WAIT_V(6); PG8_BAR; PG8_MMA(1, 1, At, B1); PG8_BAR;
;             PG8_LDB(B0, 1, 0); PG8_SCHED; PG8_LDA(At, 1, 0); PG8_STAGE(PG8_SA(0, 1), a2 + hstep, voffA);
;             PG8_WAIT_L(8); PG8_BAR; PG8_WAIT_L(0); PG8_MMA(0, 0, At, B0); PG8_BAR; PG8_SCHED;
;             PG8_LDB(B1, 1, 1); PG8_STAGE(PG8_SB(1, 0), b3, voffB);
;             PG8_BAR; PG8_WAIT_L(0); PG8_MMA(0, 1, At, B1); PG8_BAR;
;             PG8_LDA(At, 1, 1); PG8_STAGE(PG8_SA(1, 0), a3, voffA);
	s_add_u32 s44, s16, 0x40000
	s_addc_u32 s45, s17, 0
	s_add_i32 s41, s50, s24
	v_lshl_add_u64 v[144:145], s[44:45], 0, v[0:1]
	s_mov_b32 m0, s41
	s_nop 0
	global_load_lds_dwordx4 v[144:145], off
	v_lshl_add_u64 v[144:145], s[44:45], 0, v[134:135]
	s_add_i32 m0, s41, 0x2000
	s_nop 0
	global_load_lds_dwordx4 v[144:145], off
	s_waitcnt vmcnt(6)
	s_barrier
	v_mfma_f32_16x16x32_bf16 v[58:61], v[212:215], v[180:183], v[58:61]
	v_mfma_f32_16x16x32_bf16 v[50:53], v[220:223], v[180:183], v[50:53]
	v_mfma_f32_16x16x32_bf16 v[42:45], v[212:215], v[188:191], v[42:45]
	v_mfma_f32_16x16x32_bf16 v[34:37], v[220:223], v[188:191], v[34:37]
	v_mfma_f32_16x16x32_bf16 v[26:29], v[212:215], v[196:199], v[26:29]
	v_mfma_f32_16x16x32_bf16 v[18:21], v[220:223], v[196:199], v[18:21]
	v_mfma_f32_16x16x32_bf16 v[10:13], v[212:215], v[204:207], v[10:13]
	v_mfma_f32_16x16x32_bf16 v[2:5], v[220:223], v[204:207], v[2:5]
	v_mfma_f32_16x16x32_bf16 v[58:61], v[216:219], v[184:187], v[58:61]
	v_mfma_f32_16x16x32_bf16 v[50:53], v[224:227], v[184:187], v[50:53]
	v_mfma_f32_16x16x32_bf16 v[42:45], v[216:219], v[192:195], v[42:45]
	v_mfma_f32_16x16x32_bf16 v[34:37], v[224:227], v[192:195], v[34:37]
	v_mfma_f32_16x16x32_bf16 v[26:29], v[216:219], v[200:203], v[26:29]
	v_mfma_f32_16x16x32_bf16 v[18:21], v[224:227], v[200:203], v[18:21]
	v_mfma_f32_16x16x32_bf16 v[10:13], v[216:219], v[208:211], v[10:13]
	v_mfma_f32_16x16x32_bf16 v[2:5], v[224:227], v[208:211], v[2:5]
	s_add_i32 s41, 0, 0x18000
	v_add_u32_e32 v175, s41, v149
	s_barrier
	ds_read_b128 v[144:147], v175
	ds_read_b128 v[152:155], v175 offset:1024
	ds_read_b128 v[156:159], v175 offset:2048
	ds_read_b128 v[176:179], v175 offset:3072
	s_add_u32 s18, s18, 0x40000
	s_addc_u32 s19, s19, 0
	s_mov_b32 m0, s27
	v_lshl_add_u64 v[212:213], s[18:19], 0, v[138:139]
	ds_read_b128 v[180:183], v151 offset:32768
	ds_read_b128 v[184:187], v151 offset:33792
	ds_read_b128 v[188:191], v151 offset:34816
	ds_read_b128 v[192:195], v151 offset:35840
	ds_read_b128 v[196:199], v151 offset:36864
	ds_read_b128 v[200:203], v151 offset:37888
	ds_read_b128 v[204:207], v151 offset:38912
	ds_read_b128 v[208:211], v151 offset:39936
	global_load_lds_dwordx4 v[212:213], off
	v_lshl_add_u64 v[212:213], s[18:19], 0, v[136:137]
	s_mov_b32 m0, s28
	s_nop 0
	global_load_lds_dwordx4 v[212:213], off
	s_waitcnt lgkmcnt(8)
	s_barrier
	s_waitcnt lgkmcnt(0)
	v_mfma_f32_16x16x32_bf16 v[126:129], v[144:147], v[180:183], v[126:129]
	v_mfma_f32_16x16x32_bf16 v[118:121], v[156:159], v[180:183], v[118:121]
	v_mfma_f32_16x16x32_bf16 v[110:113], v[144:147], v[188:191], v[110:113]
	v_mfma_f32_16x16x32_bf16 v[102:105], v[156:159], v[188:191], v[102:105]
	v_mfma_f32_16x16x32_bf16 v[94:97], v[144:147], v[196:199], v[94:97]
	v_mfma_f32_16x16x32_bf16 v[86:89], v[156:159], v[196:199], v[86:89]
	v_mfma_f32_16x16x32_bf16 v[78:81], v[144:147], v[204:207], v[78:81]
	v_mfma_f32_16x16x32_bf16 v[70:73], v[156:159], v[204:207], v[70:73]
	v_mfma_f32_16x16x32_bf16 v[126:129], v[152:155], v[184:187], v[126:129]
	v_mfma_f32_16x16x32_bf16 v[118:121], v[176:179], v[184:187], v[118:121]
	v_mfma_f32_16x16x32_bf16 v[110:113], v[152:155], v[192:195], v[110:113]
	v_mfma_f32_16x16x32_bf16 v[102:105], v[176:179], v[192:195], v[102:105]
	v_mfma_f32_16x16x32_bf16 v[94:97], v[152:155], v[200:203], v[94:97]
	v_mfma_f32_16x16x32_bf16 v[86:89], v[176:179], v[200:203], v[86:89]
	v_mfma_f32_16x16x32_bf16 v[78:81], v[152:155], v[208:211], v[78:81]
	v_mfma_f32_16x16x32_bf16 v[70:73], v[176:179], v[208:211], v[70:73]
	s_barrier
	s_add_i32 s18, 0, 0x1c000
	s_add_i32 s19, s41, s24
	v_add_u32_e32 v175, s18, v149
	v_lshl_add_u64 v[228:229], v[228:229], 0, s[70:71]
	s_mov_b32 m0, s19
	ds_read_b128 v[212:215], v175
	ds_read_b128 v[216:219], v175 offset:1024
	ds_read_b128 v[220:223], v175 offset:2048
	ds_read_b128 v[224:227], v175 offset:3072
	global_load_lds_dwordx4 v[228:229], off
	v_lshl_add_u64 v[228:229], v[230:231], 0, s[70:71]
	s_add_i32 m0, s19, 0x2000
	s_nop 0
	global_load_lds_dwordx4 v[228:229], off
	s_barrier
	s_waitcnt lgkmcnt(0)
	v_mfma_f32_16x16x32_bf16 v[122:125], v[212:215], v[180:183], v[122:125]
	v_mfma_f32_16x16x32_bf16 v[114:117], v[220:223], v[180:183], v[114:117]
	v_mfma_f32_16x16x32_bf16 v[106:109], v[212:215], v[188:191], v[106:109]
	v_mfma_f32_16x16x32_bf16 v[98:101], v[220:223], v[188:191], v[98:101]
	v_mfma_f32_16x16x32_bf16 v[90:93], v[212:215], v[196:199], v[90:93]
	v_mfma_f32_16x16x32_bf16 v[82:85], v[220:223], v[196:199], v[82:85]
	v_mfma_f32_16x16x32_bf16 v[74:77], v[212:215], v[204:207], v[74:77]
	v_mfma_f32_16x16x32_bf16 v[66:69], v[220:223], v[204:207], v[66:69]
	v_mfma_f32_16x16x32_bf16 v[122:125], v[216:219], v[184:187], v[122:125]
	v_mfma_f32_16x16x32_bf16 v[114:117], v[224:227], v[184:187], v[114:117]
	v_mfma_f32_16x16x32_bf16 v[106:109], v[216:219], v[192:195], v[106:109]
	v_mfma_f32_16x16x32_bf16 v[98:101], v[224:227], v[192:195], v[98:101]
	v_mfma_f32_16x16x32_bf16 v[90:93], v[216:219], v[200:203], v[90:93]
	v_mfma_f32_16x16x32_bf16 v[82:85], v[224:227], v[200:203], v[82:85]
	v_mfma_f32_16x16x32_bf16 v[74:77], v[216:219], v[208:211], v[74:77]
	v_mfma_f32_16x16x32_bf16 v[66:69], v[224:227], v[208:211], v[66:69]
	s_mov_b32 m0, s29
	v_lshl_add_u64 v[228:229], v[232:233], 0, s[70:71]
	s_barrier
	ds_read_b128 v[180:183], v151 offset:49152
	ds_read_b128 v[184:187], v151 offset:50176
	ds_read_b128 v[188:191], v151 offset:51200
	ds_read_b128 v[192:195], v151 offset:52224
	ds_read_b128 v[196:199], v151 offset:53248
	ds_read_b128 v[200:203], v151 offset:54272
	ds_read_b128 v[204:207], v151 offset:55296
	ds_read_b128 v[208:211], v151 offset:56320
	global_load_lds_dwordx4 v[228:229], off
	v_lshl_add_u64 v[228:229], v[234:235], 0, s[70:71]
	s_mov_b32 m0, s30
	s_nop 0
	global_load_lds_dwordx4 v[228:229], off
	s_barrier
; #define PG8_STAGE(bufoff, gbase, voff) do { _Pragma("unroll") for (int _i = 0; _i < 2; ++_i) \
;         __builtin_amdgcn_global_load_lds((const unsigned*)((const char*)(gbase) + (voff)[_i]), (PG8_LAS unsigned*)(lds + (bufoff) + ldsw + _i * 8192), 16, 0, 0); } while (0)
; #define PG8_MMA(ai, bj, At, Bt) do { __builtin_amdgcn_s_setprio(1); _Pragma("unroll") for (int m = 0; m < 4; ++m) _Pragma("unroll") for (int n = 0; n < 2; ++n) _Pragma("unroll") for (int k = 0; k < 2; ++k) \
;         acc[ai][bj][m][n] = __builtin_amdgcn_mfma_f32_16x16x32_bf16(Bt[n][k], At[m][k], acc[ai][bj][m][n], 0, 0, 0); __builtin_amdgcn_s_setprio(0); } while (0)
; #define PG8_WAIT_V(n) asm volatile("s_waitcnt vmcnt(" #n ")" ::: "memory")
; #define PG8_WAIT_L(n) asm volatile("s_waitcnt lgkmcnt(" #n ")" ::: "memory")
; #define PG8_BAR __builtin_amdgcn_s_barrier()
; #define PG8_SCHED __builtin_amdgcn_sched_barrier(0)
; __device__ __forceinline__ unsigned pk2(float lo, float hi) { return pg8::cvt_pk_bf16(lo, hi); }
; __device__ __forceinline__ float silu(float x) { return x * __builtin_amdgcn_rcpf(1.0f + __expf(-x)); }
; template <class Epi, class Sched>
; __device__ __forceinline__ void gemm_phase(PG8_LAS unsigned char* lds, const Gemm g, const Sched& S, const Epi& E) {
;     ...
;             PG8_BAR; PG8_WAIT_L(0); PG8_MMA(1, 0, At, B0); PG8_BAR; PG8_SCHED;
;             PG8_STAGE(PG8_SB(1, 1), b3 + hstep, voffB);
;             PG8_WAIT_V(6); PG8_BAR; PG8_MMA(1, 1, At, B1); PG8_BAR;
;     __device__ __forceinline__ void operator()(const f32x4 (&acc)[2][2][4][2], const pg8::Unit& u, int wr, int wc, int fr, int fq) const {
;         const int row0 = u.pm * 256 + wr * 64 + fr, col0 = u.pn * 128 + wc * 32 + 8 * fq;
; #pragma unroll
;         for (int ai = 0; ai < 2; ++ai)
; #pragma unroll
;             for (int m = 0; m < 4; ++m) {
;                 bf16_t* p = O + (size_t)(row0 + ai * 128 + m * 16) * FF + col0;
;                 const f32x4 g0 = acc[ai][0][m][0], g1 = acc[ai][0][m][1], u0 = acc[ai][1][m][0], u1 = acc[ai][1][m][1];
;                 u32x4 w;
;                 w.x = pk2(silu(g0[0]) * u0[0], silu(g0[1]) * u0[1]); w.y = pk2(silu(g0[2]) * u0[2], silu(g0[3]) * u0[3]);
;                 w.z = pk2(silu(g1[0]) * u1[0], silu(g1[1]) * u1[1]); w.w = pk2(silu(g1[2]) * u1[2], silu(g1[3]) * u1[3]);
;                 *(u32x4*)p = w;
;             }
	s_waitcnt lgkmcnt(0)
	v_mfma_f32_16x16x32_bf16 v[62:65], v[144:147], v[180:183], v[62:65]
	v_mfma_f32_16x16x32_bf16 v[54:57], v[156:159], v[180:183], v[54:57]
	v_mfma_f32_16x16x32_bf16 v[46:49], v[144:147], v[188:191], v[46:49]
	v_mfma_f32_16x16x32_bf16 v[38:41], v[156:159], v[188:191], v[38:41]
	v_mfma_f32_16x16x32_bf16 v[30:33], v[144:147], v[196:199], v[30:33]
	v_mfma_f32_16x16x32_bf16 v[22:25], v[156:159], v[196:199], v[22:25]
	v_mfma_f32_16x16x32_bf16 v[14:17], v[144:147], v[204:207], v[14:17]
	v_mfma_f32_16x16x32_bf16 v[6:9], v[156:159], v[204:207], v[6:9]
	v_mfma_f32_16x16x32_bf16 v[62:65], v[152:155], v[184:187], v[62:65]
	v_mfma_f32_16x16x32_bf16 v[54:57], v[176:179], v[184:187], v[54:57]
	v_mfma_f32_16x16x32_bf16 v[46:49], v[152:155], v[192:195], v[46:49]
	v_mfma_f32_16x16x32_bf16 v[38:41], v[176:179], v[192:195], v[38:41]
	v_mfma_f32_16x16x32_bf16 v[30:33], v[152:155], v[200:203], v[30:33]
	v_mfma_f32_16x16x32_bf16 v[22:25], v[176:179], v[200:203], v[22:25]
	v_mfma_f32_16x16x32_bf16 v[14:17], v[152:155], v[208:211], v[14:17]
	v_mfma_f32_16x16x32_bf16 v[6:9], v[176:179], v[208:211], v[6:9]
	s_barrier
	s_add_u32 s16, s16, 0x40080
	s_addc_u32 s17, s17, 0
	s_add_i32 s18, s18, s24
	v_lshl_add_u64 v[144:145], s[16:17], 0, v[0:1]
	s_mov_b32 m0, s18
	s_nop 0
	global_load_lds_dwordx4 v[144:145], off
	v_lshl_add_u64 v[144:145], s[16:17], 0, v[134:135]
	s_add_i32 m0, s18, 0x2000
	s_nop 0
	global_load_lds_dwordx4 v[144:145], off
	s_waitcnt vmcnt(6)
	s_barrier
	v_mfma_f32_16x16x32_bf16 v[58:61], v[212:215], v[180:183], v[58:61]
	v_mfma_f32_16x16x32_bf16 v[50:53], v[220:223], v[180:183], v[50:53]
	v_mfma_f32_16x16x32_bf16 v[42:45], v[212:215], v[188:191], v[42:45]
	v_mfma_f32_16x16x32_bf16 v[34:37], v[220:223], v[188:191], v[34:37]
	v_mfma_f32_16x16x32_bf16 v[26:29], v[212:215], v[196:199], v[26:29]
	v_mfma_f32_16x16x32_bf16 v[18:21], v[220:223], v[196:199], v[18:21]
	v_mfma_f32_16x16x32_bf16 v[10:13], v[212:215], v[204:207], v[10:13]
	v_mfma_f32_16x16x32_bf16 v[2:5], v[220:223], v[204:207], v[2:5]
	v_mfma_f32_16x16x32_bf16 v[58:61], v[216:219], v[184:187], v[58:61]
	v_mfma_f32_16x16x32_bf16 v[50:53], v[224:227], v[184:187], v[50:53]
	v_mfma_f32_16x16x32_bf16 v[42:45], v[216:219], v[192:195], v[42:45]
	v_mfma_f32_16x16x32_bf16 v[34:37], v[224:227], v[192:195], v[34:37]
	v_mfma_f32_16x16x32_bf16 v[26:29], v[216:219], v[200:203], v[26:29]
	v_mfma_f32_16x16x32_bf16 v[18:21], v[224:227], v[200:203], v[18:21]
	v_mfma_f32_16x16x32_bf16 v[10:13], v[216:219], v[208:211], v[10:13]
	v_mfma_f32_16x16x32_bf16 v[2:5], v[224:227], v[208:211], v[2:5]
	s_add_i32 s40, s40, 2
	s_add_u32 s14, s14, 0x100
	s_addc_u32 s15, s15, 0
	s_add_u32 s38, s38, 0x100
	s_addc_u32 s39, s39, 0
	s_cmp_gt_u32 s40, 13
	s_barrier
	s_cbranch_scc0 .LBB0_1129
	v_mul_f32_e32 v153, 0xbfb8aa3b, v126
	v_exp_f32_e32 v153, v153
	v_lshl_or_b32 v146, s34, 7, v150
	v_lshl_add_u32 v152, s35, 8, v148
	v_ashrrev_i32_e32 v147, 31, v146
	v_add_f32_e32 v153, 1.0, v153
	v_rcp_f32_e32 v153, v153
	v_mov_b64_e32 v[144:145], s[0:1]
	v_mad_i64_i32 v[154:155], s[14:15], v152, s52, v[144:145]
	v_mul_f32_e32 v126, v126, v153
	v_mul_f32_e32 v122, v126, v122
	v_mul_f32_e32 v126, 0xbfb8aa3b, v127
	v_exp_f32_e32 v126, v126
	v_lshlrev_b64 v[146:147], 1, v[146:147]
	v_lshl_add_u64 v[154:155], v[154:155], 0, v[146:147]
	s_and_b64 vcc, exec, s[4:5]
	v_add_f32_e32 v126, 1.0, v126
	v_rcp_f32_e32 v126, v126
	s_mov_b32 s34, s6
	s_mov_b32 s35, s8
	s_mov_b64 s[16:17], s[12:13]
	v_mul_f32_e32 v126, v127, v126
	v_mul_f32_e32 v123, v126, v123
	v_cvt_pk_bf16_f32 v122, v122, v123
	v_mul_f32_e32 v123, 0xbfb8aa3b, v128
	v_exp_f32_e32 v123, v123
	s_nop 0
	v_add_f32_e32 v123, 1.0, v123
	v_rcp_f32_e32 v123, v123
	s_nop 0
	v_mul_f32_e32 v123, v128, v123
	v_mul_f32_e32 v123, v123, v124
	v_mul_f32_e32 v124, 0xbfb8aa3b, v129
	v_exp_f32_e32 v124, v124
	s_nop 0
	v_add_f32_e32 v124, 1.0, v124
	v_rcp_f32_e32 v124, v124
	s_nop 0
	v_mul_f32_e32 v124, v129, v124
	v_mul_f32_e32 v124, v124, v125
	v_cvt_pk_bf16_f32 v123, v123, v124
	v_mul_f32_e32 v124, 0xbfb8aa3b, v118
	v_exp_f32_e32 v124, v124
	s_nop 0
	v_add_f32_e32 v124, 1.0, v124
	v_rcp_f32_e32 v124, v124
	s_nop 0
	v_mul_f32_e32 v118, v118, v124
	v_mul_f32_e32 v114, v118, v114
	v_mul_f32_e32 v118, 0xbfb8aa3b, v119
	v_exp_f32_e32 v118, v118
	s_nop 0
	v_add_f32_e32 v118, 1.0, v118
	v_rcp_f32_e32 v118, v118
	s_nop 0
	v_mul_f32_e32 v118, v119, v118
	v_mul_f32_e32 v115, v118, v115
	v_cvt_pk_bf16_f32 v124, v114, v115
	v_mul_f32_e32 v114, 0xbfb8aa3b, v120
	v_exp_f32_e32 v114, v114
	v_mul_f32_e32 v115, 0xbfb8aa3b, v121
	v_exp_f32_e32 v115, v115
	v_add_f32_e32 v114, 1.0, v114
	v_rcp_f32_e32 v114, v114
	v_add_f32_e32 v115, 1.0, v115
	v_rcp_f32_e32 v115, v115
	v_mul_f32_e32 v114, v120, v114
	v_mul_f32_e32 v114, v114, v116
	v_mul_f32_e32 v116, 0xbfb8aa3b, v110
	v_exp_f32_e32 v116, v116
	v_mul_f32_e32 v115, v121, v115
	v_mul_f32_e32 v115, v115, v117
	v_cvt_pk_bf16_f32 v125, v114, v115
	v_add_f32_e32 v116, 1.0, v116
	v_rcp_f32_e32 v116, v116
	global_store_dwordx4 v[154:155], v[122:125], off
	v_or_b32_e32 v114, 16, v152
	v_mad_i64_i32 v[114:115], s[14:15], v114, s52, v[144:145]
	v_mul_f32_e32 v110, v110, v116
	v_mul_f32_e32 v106, v110, v106
	v_mul_f32_e32 v110, 0xbfb8aa3b, v111
	v_exp_f32_e32 v110, v110
	v_lshl_add_u64 v[114:115], v[114:115], 0, v[146:147]
	v_add_f32_e32 v110, 1.0, v110
	v_rcp_f32_e32 v110, v110
	s_nop 0
	v_mul_f32_e32 v110, v111, v110
	v_mul_f32_e32 v107, v110, v107
	v_cvt_pk_bf16_f32 v106, v106, v107
	v_mul_f32_e32 v107, 0xbfb8aa3b, v112
	v_exp_f32_e32 v107, v107
	s_nop 0
	v_add_f32_e32 v107, 1.0, v107
	v_rcp_f32_e32 v107, v107
	s_nop 0
	v_mul_f32_e32 v107, v112, v107
; __device__ __forceinline__ unsigned pk2(float lo, float hi) { return pg8::cvt_pk_bf16(lo, hi); }
; __device__ __forceinline__ float silu(float x) { return x * __builtin_amdgcn_rcpf(1.0f + __expf(-x)); }
;     __device__ __forceinline__ void operator()(const f32x4 (&acc)[2][2][4][2], const pg8::Unit& u, int wr, int wc, int fr, int fq) const {
;         const int row0 = u.pm * 256 + wr * 64 + fr, col0 = u.pn * 128 + wc * 32 + 8 * fq;
; #pragma unroll
;         for (int ai = 0; ai < 2; ++ai)
; #pragma unroll
;             for (int m = 0; m < 4; ++m) {
;                 bf16_t* p = O + (size_t)(row0 + ai * 128 + m * 16) * FF + col0;
;                 const f32x4 g0 = acc[ai][0][m][0], g1 = acc[ai][0][m][1], u0 = acc[ai][1][m][0], u1 = acc[ai][1][m][1];
;                 u32x4 w;
;                 w.x = pk2(silu(g0[0]) * u0[0], silu(g0[1]) * u0[1]); w.y = pk2(silu(g0[2]) * u0[2], silu(g0[3]) * u0[3]);
;                 w.z = pk2(silu(g1[0]) * u1[0], silu(g1[1]) * u1[1]); w.w = pk2(silu(g1[2]) * u1[2], silu(g1[3]) * u1[3]);
;                 *(u32x4*)p = w;
;             }
	v_mul_f32_e32 v107, v107, v108
	v_mul_f32_e32 v108, 0xbfb8aa3b, v113
	v_exp_f32_e32 v108, v108
	s_nop 0
	v_add_f32_e32 v108, 1.0, v108
	v_rcp_f32_e32 v108, v108
	s_nop 0
	v_mul_f32_e32 v108, v113, v108
	v_mul_f32_e32 v108, v108, v109
	v_cvt_pk_bf16_f32 v107, v107, v108
	v_mul_f32_e32 v108, 0xbfb8aa3b, v102
	v_exp_f32_e32 v108, v108
	s_nop 0
	v_add_f32_e32 v108, 1.0, v108
	v_rcp_f32_e32 v108, v108
	s_nop 0
	v_mul_f32_e32 v102, v102, v108
	v_mul_f32_e32 v98, v102, v98
	v_mul_f32_e32 v102, 0xbfb8aa3b, v103
	v_exp_f32_e32 v102, v102
	s_nop 0
	v_add_f32_e32 v102, 1.0, v102
	v_rcp_f32_e32 v102, v102
	s_nop 0
	v_mul_f32_e32 v102, v103, v102
	v_mul_f32_e32 v99, v102, v99
	v_cvt_pk_bf16_f32 v108, v98, v99
	v_mul_f32_e32 v98, 0xbfb8aa3b, v104
	v_exp_f32_e32 v98, v98
	v_mul_f32_e32 v99, 0xbfb8aa3b, v105
	v_exp_f32_e32 v99, v99
	v_add_f32_e32 v98, 1.0, v98
	v_rcp_f32_e32 v98, v98
	v_add_f32_e32 v99, 1.0, v99
	v_rcp_f32_e32 v99, v99
	v_mul_f32_e32 v98, v104, v98
	v_mul_f32_e32 v98, v98, v100
	v_mul_f32_e32 v100, 0xbfb8aa3b, v94
	v_exp_f32_e32 v100, v100
	v_mul_f32_e32 v99, v105, v99
	v_mul_f32_e32 v99, v99, v101
	v_cvt_pk_bf16_f32 v109, v98, v99
	v_add_f32_e32 v100, 1.0, v100
	v_rcp_f32_e32 v100, v100
	global_store_dwordx4 v[114:115], v[106:109], off
	v_or_b32_e32 v98, 32, v152
	v_mad_i64_i32 v[98:99], s[14:15], v98, s52, v[144:145]
	v_mul_f32_e32 v94, v94, v100
	v_mul_f32_e32 v90, v94, v90
	v_mul_f32_e32 v94, 0xbfb8aa3b, v95
	v_exp_f32_e32 v94, v94
	v_lshl_add_u64 v[98:99], v[98:99], 0, v[146:147]
	v_add_f32_e32 v94, 1.0, v94
	v_rcp_f32_e32 v94, v94
	s_nop 0
	v_mul_f32_e32 v94, v95, v94
	v_mul_f32_e32 v91, v94, v91
	v_cvt_pk_bf16_f32 v90, v90, v91
	v_mul_f32_e32 v91, 0xbfb8aa3b, v96
	v_exp_f32_e32 v91, v91
	s_nop 0
	v_add_f32_e32 v91, 1.0, v91
	v_rcp_f32_e32 v91, v91
	s_nop 0
	v_mul_f32_e32 v91, v96, v91
	v_mul_f32_e32 v91, v91, v92
	v_mul_f32_e32 v92, 0xbfb8aa3b, v97
	v_exp_f32_e32 v92, v92
	s_nop 0
	v_add_f32_e32 v92, 1.0, v92
	v_rcp_f32_e32 v92, v92
	s_nop 0
	v_mul_f32_e32 v92, v97, v92
	v_mul_f32_e32 v92, v92, v93
	v_cvt_pk_bf16_f32 v91, v91, v92
	v_mul_f32_e32 v92, 0xbfb8aa3b, v86
	v_exp_f32_e32 v92, v92
	s_nop 0
	v_add_f32_e32 v92, 1.0, v92
	v_rcp_f32_e32 v92, v92
	s_nop 0
	v_mul_f32_e32 v86, v86, v92
	v_mul_f32_e32 v82, v86, v82
	v_mul_f32_e32 v86, 0xbfb8aa3b, v87
	v_exp_f32_e32 v86, v86
	s_nop 0
	v_add_f32_e32 v86, 1.0, v86
	v_rcp_f32_e32 v86, v86
	s_nop 0
	v_mul_f32_e32 v86, v87, v86
	v_mul_f32_e32 v83, v86, v83
	v_cvt_pk_bf16_f32 v92, v82, v83
	v_mul_f32_e32 v82, 0xbfb8aa3b, v88
	v_exp_f32_e32 v82, v82
	v_mul_f32_e32 v83, 0xbfb8aa3b, v89
	v_exp_f32_e32 v83, v83
	v_add_f32_e32 v82, 1.0, v82
	v_rcp_f32_e32 v82, v82
	v_add_f32_e32 v83, 1.0, v83
	v_rcp_f32_e32 v83, v83
	v_mul_f32_e32 v82, v88, v82
	v_mul_f32_e32 v82, v82, v84
	v_mul_f32_e32 v84, 0xbfb8aa3b, v78
	v_exp_f32_e32 v84, v84
	v_mul_f32_e32 v83, v89, v83
	v_mul_f32_e32 v83, v83, v85
	v_cvt_pk_bf16_f32 v93, v82, v83
	v_add_f32_e32 v84, 1.0, v84
	v_rcp_f32_e32 v84, v84
	global_store_dwordx4 v[98:99], v[90:93], off
	v_or_b32_e32 v82, 48, v152
	v_mad_i64_i32 v[82:83], s[14:15], v82, s52, v[144:145]
	v_mul_f32_e32 v78, v78, v84
	v_mul_f32_e32 v74, v78, v74
	v_mul_f32_e32 v78, 0xbfb8aa3b, v79
	v_exp_f32_e32 v78, v78
	v_lshl_add_u64 v[82:83], v[82:83], 0, v[146:147]
	v_add_f32_e32 v78, 1.0, v78
	v_rcp_f32_e32 v78, v78
	s_nop 0
	v_mul_f32_e32 v78, v79, v78
	v_mul_f32_e32 v75, v78, v75
	v_cvt_pk_bf16_f32 v74, v74, v75
	v_mul_f32_e32 v75, 0xbfb8aa3b, v80
	v_exp_f32_e32 v75, v75
	s_nop 0
	v_add_f32_e32 v75, 1.0, v75
	v_rcp_f32_e32 v75, v75
	s_nop 0
	v_mul_f32_e32 v75, v80, v75
	v_mul_f32_e32 v75, v75, v76
	v_mul_f32_e32 v76, 0xbfb8aa3b, v81
	v_exp_f32_e32 v76, v76
	s_nop 0
	v_add_f32_e32 v76, 1.0, v76
	v_rcp_f32_e32 v76, v76
	s_nop 0
	v_mul_f32_e32 v76, v81, v76
	v_mul_f32_e32 v76, v76, v77
	v_cvt_pk_bf16_f32 v75, v75, v76
	v_mul_f32_e32 v76, 0xbfb8aa3b, v70
	v_exp_f32_e32 v76, v76
	s_nop 0
	v_add_f32_e32 v76, 1.0, v76
	v_rcp_f32_e32 v76, v76
	s_nop 0
	v_mul_f32_e32 v70, v70, v76
	v_mul_f32_e32 v66, v70, v66
	v_mul_f32_e32 v70, 0xbfb8aa3b, v71
	v_exp_f32_e32 v70, v70
	s_nop 0
	v_add_f32_e32 v70, 1.0, v70
	v_rcp_f32_e32 v70, v70
	s_nop 0
	v_mul_f32_e32 v70, v71, v70
	v_mul_f32_e32 v67, v70, v67
	v_cvt_pk_bf16_f32 v76, v66, v67
	v_mul_f32_e32 v66, 0xbfb8aa3b, v72
	v_exp_f32_e32 v66, v66
	v_mul_f32_e32 v67, 0xbfb8aa3b, v73
	v_exp_f32_e32 v67, v67
	v_add_f32_e32 v66, 1.0, v66
	v_rcp_f32_e32 v66, v66
	v_add_f32_e32 v67, 1.0, v67
	v_rcp_f32_e32 v67, v67
	v_mul_f32_e32 v66, v72, v66
	v_mul_f32_e32 v66, v66, v68
	v_mul_f32_e32 v68, 0xbfb8aa3b, v62
	v_exp_f32_e32 v68, v68
	v_mul_f32_e32 v67, v73, v67
	v_mul_f32_e32 v67, v67, v69
	v_cvt_pk_bf16_f32 v77, v66, v67
	v_add_f32_e32 v68, 1.0, v68
	v_rcp_f32_e32 v68, v68
	global_store_dwordx4 v[82:83], v[74:77], off
	v_add_u32_e32 v66, 0x80, v152
	v_mad_i64_i32 v[66:67], s[14:15], v66, s52, v[144:145]
	v_mul_f32_e32 v62, v62, v68
	v_mul_f32_e32 v58, v62, v58
	v_mul_f32_e32 v62, 0xbfb8aa3b, v63
	v_exp_f32_e32 v62, v62
	v_lshl_add_u64 v[66:67], v[66:67], 0, v[146:147]
	v_add_f32_e32 v62, 1.0, v62
	v_rcp_f32_e32 v62, v62
	s_nop 0
	v_mul_f32_e32 v62, v63, v62
	v_mul_f32_e32 v59, v62, v59
	v_cvt_pk_bf16_f32 v58, v58, v59
	v_mul_f32_e32 v59, 0xbfb8aa3b, v64
	v_exp_f32_e32 v59, v59
	s_nop 0
	v_add_f32_e32 v59, 1.0, v59
	v_rcp_f32_e32 v59, v59
	s_nop 0
	v_mul_f32_e32 v59, v64, v59
	v_mul_f32_e32 v59, v59, v60
	v_mul_f32_e32 v60, 0xbfb8aa3b, v65
	v_exp_f32_e32 v60, v60
	s_nop 0
	v_add_f32_e32 v60, 1.0, v60
	v_rcp_f32_e32 v60, v60
	s_nop 0
	v_mul_f32_e32 v60, v65, v60
	v_mul_f32_e32 v60, v60, v61
	v_cvt_pk_bf16_f32 v59, v59, v60
	v_mul_f32_e32 v60, 0xbfb8aa3b, v54
; #define PG8_WAIT_V(n) asm volatile("s_waitcnt vmcnt(" #n ")" ::: "memory")
; #define PG8_BAR __builtin_amdgcn_s_barrier()
; __device__ __forceinline__ unsigned pk2(float lo, float hi) { return pg8::cvt_pk_bf16(lo, hi); }
; __device__ __forceinline__ float silu(float x) { return x * __builtin_amdgcn_rcpf(1.0f + __expf(-x)); }
; template <class Epi, class Sched>
; __device__ __forceinline__ void gemm_phase(PG8_LAS unsigned char* lds, const Gemm g, const Sched& S, const Epi& E) {
;     ...
;         if (!has_next) break;
; #pragma unroll
;         for (int a = 0; a < 2; ++a)
; #pragma unroll
;             for (int b = 0; b < 2; ++b)
; #pragma unroll
;                 for (int m = 0; m < 4; ++m)
; #pragma unroll
;                     for (int n = 0; n < 2; ++n) acc[a][b][m][n] = (f32x4){0.f, 0.f, 0.f, 0.f};
;         cur = nxt; cA = nA; cB = nB; ++ui;
;     }
;     PG8_WAIT_V(0);
;     if (wr == 0) PG8_BAR;
;     PG8_BAR;
;     __device__ __forceinline__ void operator()(const f32x4 (&acc)[2][2][4][2], const pg8::Unit& u, int wr, int wc, int fr, int fq) const {
;         const int row0 = u.pm * 256 + wr * 64 + fr, col0 = u.pn * 128 + wc * 32 + 8 * fq;
; #pragma unroll
;         for (int ai = 0; ai < 2; ++ai)
; #pragma unroll
;             for (int m = 0; m < 4; ++m) {
;                 bf16_t* p = O + (size_t)(row0 + ai * 128 + m * 16) * FF + col0;
;                 const f32x4 g0 = acc[ai][0][m][0], g1 = acc[ai][0][m][1], u0 = acc[ai][1][m][0], u1 = acc[ai][1][m][1];
;                 u32x4 w;
;                 w.x = pk2(silu(g0[0]) * u0[0], silu(g0[1]) * u0[1]); w.y = pk2(silu(g0[2]) * u0[2], silu(g0[3]) * u0[3]);
;                 w.z = pk2(silu(g1[0]) * u1[0], silu(g1[1]) * u1[1]); w.w = pk2(silu(g1[2]) * u1[2], silu(g1[3]) * u1[3]);
;                 *(u32x4*)p = w;
;             }
	v_exp_f32_e32 v60, v60
	s_nop 0
	v_add_f32_e32 v60, 1.0, v60
	v_rcp_f32_e32 v60, v60
	s_nop 0
	v_mul_f32_e32 v54, v54, v60
	v_mul_f32_e32 v50, v54, v50
	v_mul_f32_e32 v54, 0xbfb8aa3b, v55
	v_exp_f32_e32 v54, v54
	s_nop 0
	v_add_f32_e32 v54, 1.0, v54
	v_rcp_f32_e32 v54, v54
	s_nop 0
	v_mul_f32_e32 v54, v55, v54
	v_mul_f32_e32 v51, v54, v51
	v_cvt_pk_bf16_f32 v60, v50, v51
	v_mul_f32_e32 v50, 0xbfb8aa3b, v56
	v_exp_f32_e32 v50, v50
	v_mul_f32_e32 v51, 0xbfb8aa3b, v57
	v_exp_f32_e32 v51, v51
	v_add_f32_e32 v50, 1.0, v50
	v_rcp_f32_e32 v50, v50
	v_add_f32_e32 v51, 1.0, v51
	v_rcp_f32_e32 v51, v51
	v_mul_f32_e32 v50, v56, v50
	v_mul_f32_e32 v50, v50, v52
	v_mul_f32_e32 v52, 0xbfb8aa3b, v46
	v_exp_f32_e32 v52, v52
	v_mul_f32_e32 v51, v57, v51
	v_mul_f32_e32 v51, v51, v53
	v_cvt_pk_bf16_f32 v61, v50, v51
	v_add_f32_e32 v52, 1.0, v52
	v_rcp_f32_e32 v52, v52
	global_store_dwordx4 v[66:67], v[58:61], off
	v_add_u32_e32 v50, 0x90, v152
	v_mad_i64_i32 v[50:51], s[14:15], v50, s52, v[144:145]
	v_mul_f32_e32 v46, v46, v52
	v_mul_f32_e32 v42, v46, v42
	v_mul_f32_e32 v46, 0xbfb8aa3b, v47
	v_exp_f32_e32 v46, v46
	v_lshl_add_u64 v[50:51], v[50:51], 0, v[146:147]
	v_add_f32_e32 v46, 1.0, v46
	v_rcp_f32_e32 v46, v46
	s_nop 0
	v_mul_f32_e32 v46, v47, v46
	v_mul_f32_e32 v43, v46, v43
	v_cvt_pk_bf16_f32 v42, v42, v43
	v_mul_f32_e32 v43, 0xbfb8aa3b, v48
	v_exp_f32_e32 v43, v43
	s_nop 0
	v_add_f32_e32 v43, 1.0, v43
	v_rcp_f32_e32 v43, v43
	s_nop 0
	v_mul_f32_e32 v43, v48, v43
	v_mul_f32_e32 v43, v43, v44
	v_mul_f32_e32 v44, 0xbfb8aa3b, v49
	v_exp_f32_e32 v44, v44
	s_nop 0
	v_add_f32_e32 v44, 1.0, v44
	v_rcp_f32_e32 v44, v44
	s_nop 0
	v_mul_f32_e32 v44, v49, v44
	v_mul_f32_e32 v44, v44, v45
	v_cvt_pk_bf16_f32 v43, v43, v44
	v_mul_f32_e32 v44, 0xbfb8aa3b, v38
	v_exp_f32_e32 v44, v44
	s_nop 0
	v_add_f32_e32 v44, 1.0, v44
	v_rcp_f32_e32 v44, v44
	s_nop 0
	v_mul_f32_e32 v38, v38, v44
	v_mul_f32_e32 v34, v38, v34
	v_mul_f32_e32 v38, 0xbfb8aa3b, v39
	v_exp_f32_e32 v38, v38
	s_nop 0
	v_add_f32_e32 v38, 1.0, v38
	v_rcp_f32_e32 v38, v38
	s_nop 0
	v_mul_f32_e32 v38, v39, v38
	v_mul_f32_e32 v35, v38, v35
	v_cvt_pk_bf16_f32 v44, v34, v35
	v_mul_f32_e32 v34, 0xbfb8aa3b, v40
	v_exp_f32_e32 v34, v34
	v_mul_f32_e32 v35, 0xbfb8aa3b, v41
	v_exp_f32_e32 v35, v35
	v_add_f32_e32 v34, 1.0, v34
	v_rcp_f32_e32 v34, v34
	v_add_f32_e32 v35, 1.0, v35
	v_rcp_f32_e32 v35, v35
	v_mul_f32_e32 v34, v40, v34
	v_mul_f32_e32 v34, v34, v36
	v_mul_f32_e32 v36, 0xbfb8aa3b, v30
	v_exp_f32_e32 v36, v36
	v_mul_f32_e32 v35, v41, v35
	v_mul_f32_e32 v35, v35, v37
	v_cvt_pk_bf16_f32 v45, v34, v35
	v_add_f32_e32 v36, 1.0, v36
	v_rcp_f32_e32 v36, v36
	global_store_dwordx4 v[50:51], v[42:45], off
	v_add_u32_e32 v34, 0xa0, v152
	v_mad_i64_i32 v[34:35], s[14:15], v34, s52, v[144:145]
	v_mul_f32_e32 v30, v30, v36
	v_mul_f32_e32 v26, v30, v26
	v_mul_f32_e32 v30, 0xbfb8aa3b, v31
	v_exp_f32_e32 v30, v30
	v_lshl_add_u64 v[34:35], v[34:35], 0, v[146:147]
	v_add_f32_e32 v30, 1.0, v30
	v_rcp_f32_e32 v30, v30
	s_nop 0
	v_mul_f32_e32 v30, v31, v30
	v_mul_f32_e32 v27, v30, v27
	v_cvt_pk_bf16_f32 v26, v26, v27
	v_mul_f32_e32 v27, 0xbfb8aa3b, v32
	v_exp_f32_e32 v27, v27
	s_nop 0
	v_add_f32_e32 v27, 1.0, v27
	v_rcp_f32_e32 v27, v27
	s_nop 0
	v_mul_f32_e32 v27, v32, v27
	v_mul_f32_e32 v27, v27, v28
	v_mul_f32_e32 v28, 0xbfb8aa3b, v33
	v_exp_f32_e32 v28, v28
	s_nop 0
	v_add_f32_e32 v28, 1.0, v28
	v_rcp_f32_e32 v28, v28
	s_nop 0
	v_mul_f32_e32 v28, v33, v28
	v_mul_f32_e32 v28, v28, v29
	v_cvt_pk_bf16_f32 v27, v27, v28
	v_mul_f32_e32 v28, 0xbfb8aa3b, v22
	v_exp_f32_e32 v28, v28
	s_nop 0
	v_add_f32_e32 v28, 1.0, v28
	v_rcp_f32_e32 v28, v28
	s_nop 0
	v_mul_f32_e32 v22, v22, v28
	v_mul_f32_e32 v18, v22, v18
	v_mul_f32_e32 v22, 0xbfb8aa3b, v23
	v_exp_f32_e32 v22, v22
	s_nop 0
	v_add_f32_e32 v22, 1.0, v22
	v_rcp_f32_e32 v22, v22
	s_nop 0
	v_mul_f32_e32 v22, v23, v22
	v_mul_f32_e32 v19, v22, v19
	v_cvt_pk_bf16_f32 v28, v18, v19
	v_mul_f32_e32 v18, 0xbfb8aa3b, v24
	v_exp_f32_e32 v18, v18
	v_mul_f32_e32 v19, 0xbfb8aa3b, v25
	v_exp_f32_e32 v19, v19
	v_add_f32_e32 v18, 1.0, v18
	v_rcp_f32_e32 v18, v18
	v_add_f32_e32 v19, 1.0, v19
	v_rcp_f32_e32 v19, v19
	v_mul_f32_e32 v18, v24, v18
	v_mul_f32_e32 v18, v18, v20
	v_mul_f32_e32 v20, 0xbfb8aa3b, v14
	v_exp_f32_e32 v20, v20
	v_mul_f32_e32 v19, v25, v19
	v_mul_f32_e32 v19, v19, v21
	v_cvt_pk_bf16_f32 v29, v18, v19
	v_add_f32_e32 v20, 1.0, v20
	v_rcp_f32_e32 v20, v20
	global_store_dwordx4 v[34:35], v[26:29], off
	v_add_u32_e32 v18, 0xb0, v152
	v_mad_i64_i32 v[18:19], s[14:15], v18, s52, v[144:145]
	v_mul_f32_e32 v14, v14, v20
	v_mul_f32_e32 v10, v14, v10
	v_mul_f32_e32 v14, 0xbfb8aa3b, v15
	v_exp_f32_e32 v14, v14
	v_lshl_add_u64 v[18:19], v[18:19], 0, v[146:147]
	s_mov_b64 s[14:15], s[10:11]
	v_add_f32_e32 v14, 1.0, v14
	v_rcp_f32_e32 v14, v14
	s_nop 0
	v_mul_f32_e32 v14, v15, v14
	v_mul_f32_e32 v11, v14, v11
	v_cvt_pk_bf16_f32 v10, v10, v11
	v_mul_f32_e32 v11, 0xbfb8aa3b, v16
	v_exp_f32_e32 v11, v11
	s_nop 0
	v_add_f32_e32 v11, 1.0, v11
	v_rcp_f32_e32 v11, v11
	s_nop 0
	v_mul_f32_e32 v11, v16, v11
	v_mul_f32_e32 v11, v11, v12
	v_mul_f32_e32 v12, 0xbfb8aa3b, v17
	v_exp_f32_e32 v12, v12
	s_nop 0
	v_add_f32_e32 v12, 1.0, v12
	v_rcp_f32_e32 v12, v12
	s_nop 0
	v_mul_f32_e32 v12, v17, v12
	v_mul_f32_e32 v12, v12, v13
	v_cvt_pk_bf16_f32 v11, v11, v12
	v_mul_f32_e32 v12, 0xbfb8aa3b, v6
	v_exp_f32_e32 v12, v12
	s_nop 0
	v_add_f32_e32 v12, 1.0, v12
	v_rcp_f32_e32 v12, v12
	s_nop 0
	v_mul_f32_e32 v6, v6, v12
	v_mul_f32_e32 v2, v6, v2
	v_mul_f32_e32 v6, 0xbfb8aa3b, v7
	v_exp_f32_e32 v6, v6
	s_nop 0
	v_add_f32_e32 v6, 1.0, v6
	v_rcp_f32_e32 v6, v6
	s_nop 0
	v_mul_f32_e32 v6, v7, v6
	v_mul_f32_e32 v3, v6, v3
	v_cvt_pk_bf16_f32 v12, v2, v3
	v_mul_f32_e32 v2, 0xbfb8aa3b, v8
	v_mul_f32_e32 v3, 0xbfb8aa3b, v9
	v_exp_f32_e32 v2, v2
	v_exp_f32_e32 v3, v3
	v_add_f32_e32 v2, 1.0, v2
	v_add_f32_e32 v3, 1.0, v3
	v_rcp_f32_e32 v2, v2
	v_rcp_f32_e32 v3, v3
	v_mul_f32_e32 v2, v8, v2
	v_mul_f32_e32 v3, v9, v3
	v_mul_f32_e32 v2, v2, v4
	v_mul_f32_e32 v3, v3, v5
	v_cvt_pk_bf16_f32 v13, v2, v3
	global_store_dwordx4 v[18:19], v[10:13], off
	s_cbranch_vccz .LBB0_1126
	s_waitcnt vmcnt(0)
	s_cmpk_gt_u32 s2, 0xff
	s_cbranch_scc1 .LBB0_1133
	s_barrier
